# v28 + P9 body rewritten: bu through LDS as f32 (transposed S1 MFMA, no cvt/unpack), X aliases bu region
# baseline (speedup 1.0000x reference)
; #define LAS __attribute__((address_space(3)))
; __device__ __forceinline__ unsigned pk2(float lo, float hi) { f32x2 v = {lo, hi}; nbf2 r = __builtin_convertvector(v, nbf2); return __builtin_bit_cast(unsigned, r); }
; #define WAVE_LDS_FENCE() asm volatile("s_waitcnt lgkmcnt(0)" ::: "memory")
; __device__ __forceinline__ void s5_out_phase(LAS unsigned char* lds, const bf16_t* UZ, const unsigned char* ws, const float* dskip, bf16_t* YG) {
;     ...
;             for (int nt = 0; nt < 8; ++nt) {
;                 const f32x4 z = {0.f, 0.f, 0.f, 0.f};
;                 const f32x4 cf = __builtin_amdgcn_mfma_f32_16x16x16bf16_1k(Uf[mf], Bf[0][nt], z, 0, 0, 0);
;                 const f32x4 cb = __builtin_amdgcn_mfma_f32_16x16x16bf16_1k(Uf[mb], Bf[1][nt], z, 0, 0, 0);
;                 u32x2 wf, wb; wf.x = pk2(cf[0], cf[1]); wf.y = pk2(cf[2], cf[3]); wb.x = pk2(cb[0], cb[1]); wb.y = pk2(cb[2], cb[3]);
;                 *(LAS u32x2*)(wl + nt * 640 + wofs) = wf;
;                 *(LAS u32x2*)(wl + BUT_BYTES + nt * 640 + wofs) = wb;
;             }
;             WAVE_LDS_FENCE();
;             const LAS unsigned char* rp = wl + lane * 80;
;             const u32x4 fre0 = *(const LAS u32x4*)(rp), fre1 = *(const LAS u32x4*)(rp + 16), fim0 = *(const LAS u32x4*)(rp + 32), fim1 = *(const LAS u32x4*)(rp + 48);
;             const u32x4 bre0 = *(const LAS u32x4*)(rp + BUT_BYTES), bre1 = *(const LAS u32x4*)(rp + BUT_BYTES + 16), bim0 = *(const LAS u32x4*)(rp + BUT_BYTES + 32), bim1 = *(const LAS u32x4*)(rp + BUT_BYTES + 48);
;             LAS unsigned char* xf = wl + 2 * BUT_BYTES; LAS unsigned char* xbk = xf + XB_BYTES;
; #pragma unroll
;             for (int rr = 0; rr < 16; ++rr) {
;                 const int r = rr, rb = 15 - rr;
;                 { const f32x2 bb = {bf_at(fre0, fre1, r), bf_at(fim0, fim1, r)};
;                   const f32x2 n2 = cmac((f32x2){xfr, xfi}, (f32x2){ap[0].x, ap[0].x}, (f32x2){-ap[0].y, ap[0].y}, bb); xfr = n2.x; xfi = n2.y;
;                   *(LAS unsigned*)(xf + r * XB_PITCH + lane * 4) = pk2(n2.x, n2.y); }
;                 { const f32x2 bb = {bf_at(bre0, bre1, rb), bf_at(bim0, bim1, rb)};
;                   const f32x2 n2 = cmac((f32x2){xbr, xbi}, (f32x2){ap[1].x, ap[1].x}, (f32x2){-ap[1].y, ap[1].y}, bb); xbr = n2.x; xbi = n2.y;
;                   *(LAS unsigned*)(xbk + rb * XB_PITCH + lane * 4) = pk2(n2.x, n2.y); }
;             }
.LBB0_755:
	v_and_b32_e32 v143, 63, v192
	v_mov_b32_e32 v187, 0x8c
	v_mad_u32_u24 v139, v143, v187, v103
	v_lshrrev_b32_e32 v187, 4, v143
	v_and_b32_e32 v143, 15, v143
	v_mov_b32_e32 v136, 0xe0
	v_mad_u32_u24 v136, v187, v136, v103
	v_lshl_add_u32 v136, v143, 2, v136
	v_mov_b64_e32 v[188:189], v[44:45]
	v_mov_b64_e32 v[190:191], v[46:47]
	v_mfma_f32_16x16x16_bf16 v[226:229], v[60:61], v[172:173], 0
	v_mfma_f32_16x16x16_bf16 v[230:233], v[76:77], v[116:117], 0
	v_mfma_f32_16x16x16_bf16 v[234:237], v[62:63], v[172:173], 0
	v_mfma_f32_16x16x16_bf16 v[238:241], v[78:79], v[116:117], 0
	s_nop 4
	ds_write_b64 v136, v[226:227]
	s_nop 2
	ds_write_b64 v136, v[228:229] offset:144
	v_mfma_f32_16x16x16_bf16 v[242:245], v[64:65], v[172:173], 0
	s_nop 0
	ds_write_b64 v136, v[230:231] offset:9216
	ds_write_b64 v136, v[232:233] offset:9360
	v_mfma_f32_16x16x16_bf16 v[246:249], v[80:81], v[116:117], 0
	ds_write_b64 v136, v[234:235] offset:1152
	ds_write_b64 v136, v[236:237] offset:1296
	v_mfma_f32_16x16x16_bf16 v[226:229], v[66:67], v[172:173], 0
	ds_write_b64 v136, v[238:239] offset:10368
	ds_write_b64 v136, v[240:241] offset:10512
	v_mfma_f32_16x16x16_bf16 v[230:233], v[82:83], v[116:117], 0
	ds_write_b64 v136, v[242:243] offset:2304
	ds_write_b64 v136, v[244:245] offset:2448
	v_mfma_f32_16x16x16_bf16 v[234:237], v[68:69], v[172:173], 0
	ds_write_b64 v136, v[246:247] offset:11520
	ds_write_b64 v136, v[248:249] offset:11664
	v_mfma_f32_16x16x16_bf16 v[238:241], v[84:85], v[116:117], 0
	ds_write_b64 v136, v[226:227] offset:3456
	ds_write_b64 v136, v[228:229] offset:3600
	v_mfma_f32_16x16x16_bf16 v[242:245], v[70:71], v[172:173], 0
	ds_write_b64 v136, v[230:231] offset:12672
	ds_write_b64 v136, v[232:233] offset:12816
	v_mfma_f32_16x16x16_bf16 v[246:249], v[86:87], v[116:117], 0
	ds_write_b64 v136, v[234:235] offset:4608
	ds_write_b64 v136, v[236:237] offset:4752
	v_mfma_f32_16x16x16_bf16 v[226:229], v[72:73], v[172:173], 0
	ds_write_b64 v136, v[238:239] offset:13824
	ds_write_b64 v136, v[240:241] offset:13968
	v_mfma_f32_16x16x16_bf16 v[230:233], v[88:89], v[116:117], 0
	ds_write_b64 v136, v[242:243] offset:5760
	ds_write_b64 v136, v[244:245] offset:5904
	v_mfma_f32_16x16x16_bf16 v[234:237], v[74:75], v[172:173], 0
	ds_write_b64 v136, v[246:247] offset:14976
	ds_write_b64 v136, v[248:249] offset:15120
	v_mfma_f32_16x16x16_bf16 v[238:241], v[90:91], v[116:117], 0
	ds_write_b64 v136, v[226:227] offset:6912
	ds_write_b64 v136, v[228:229] offset:7056
	ds_write_b64 v136, v[230:231] offset:16128
	ds_write_b64 v136, v[232:233] offset:16272
	s_nop 0
	ds_write_b64 v136, v[234:235] offset:8064
	ds_write_b64 v136, v[236:237] offset:8208
	s_nop 0
	ds_write_b64 v136, v[238:239] offset:17280
	ds_write_b64 v136, v[240:241] offset:17424
	ds_read_b128 v[194:197], v139
	ds_read_b128 v[198:201], v139 offset:9328
	ds_read_b128 v[202:205], v139 offset:16
	ds_read_b128 v[206:209], v139 offset:9312
	ds_read_b128 v[210:213], v139 offset:32
	ds_read_b128 v[214:217], v139 offset:9296
	ds_read_b128 v[218:221], v139 offset:48
	ds_read_b128 v[222:225], v139 offset:9280
	ds_read_b128 v[226:229], v139 offset:64
	ds_read_b128 v[230:233], v139 offset:9264
	ds_read_b128 v[234:237], v139 offset:80
	ds_read_b128 v[238:241], v139 offset:9248
	ds_read_b128 v[242:245], v139 offset:96
	ds_read_b128 v[246:249], v139 offset:9232
	ds_read_b128 v[250:253], v139 offset:112
	s_waitcnt lgkmcnt(14)
	v_pk_fma_f32 v[194:195], v[150:151], v[188:189], v[194:195]
	s_waitcnt lgkmcnt(13)
	v_pk_fma_f32 v[200:201], v[152:153], v[190:191], v[200:201]
	v_pk_fma_f32 v[188:189], v[16:17], v[188:189], v[194:195] op_sel:[0,1,0] op_sel_hi:[1,0,1]
	v_pk_fma_f32 v[190:191], v[36:37], v[190:191], v[200:201] op_sel:[0,1,0] op_sel_hi:[1,0,1]
	v_cvt_pk_bf16_f32 v114, v188, v189
	v_cvt_pk_bf16_f32 v128, v190, v191
	ds_write_b32 v103, v114
	ds_write_b32 v103, v128 offset:8432
	v_pk_fma_f32 v[196:197], v[150:151], v[188:189], v[196:197]
	v_pk_fma_f32 v[198:199], v[152:153], v[190:191], v[198:199]
	v_pk_fma_f32 v[188:189], v[16:17], v[188:189], v[196:197] op_sel:[0,1,0] op_sel_hi:[1,0,1]
	v_pk_fma_f32 v[190:191], v[36:37], v[190:191], v[198:199] op_sel:[0,1,0] op_sel_hi:[1,0,1]
	v_cvt_pk_bf16_f32 v119, v188, v189
	v_cvt_pk_bf16_f32 v131, v190, v191
	ds_write_b32 v103, v119 offset:272
	ds_write_b32 v103, v131 offset:8160
	ds_read_b128 v[194:197], v139 offset:9216
	s_waitcnt lgkmcnt(15)
	v_pk_fma_f32 v[202:203], v[150:151], v[188:189], v[202:203]
	v_pk_fma_f32 v[208:209], v[152:153], v[190:191], v[208:209]
	v_pk_fma_f32 v[188:189], v[16:17], v[188:189], v[202:203] op_sel:[0,1,0] op_sel_hi:[1,0,1]
	v_pk_fma_f32 v[190:191], v[36:37], v[190:191], v[208:209] op_sel:[0,1,0] op_sel_hi:[1,0,1]
	v_cvt_pk_bf16_f32 v121, v188, v189
	v_cvt_pk_bf16_f32 v132, v190, v191
	ds_write_b32 v103, v121 offset:544
	ds_write_b32 v103, v132 offset:7888
	v_pk_fma_f32 v[204:205], v[150:151], v[188:189], v[204:205]
	v_pk_fma_f32 v[206:207], v[152:153], v[190:191], v[206:207]
	v_pk_fma_f32 v[188:189], v[16:17], v[188:189], v[204:205] op_sel:[0,1,0] op_sel_hi:[1,0,1]
	v_pk_fma_f32 v[190:191], v[36:37], v[190:191], v[206:207] op_sel:[0,1,0] op_sel_hi:[1,0,1]
	v_cvt_pk_bf16_f32 v127, v188, v189
	v_cvt_pk_bf16_f32 v135, v190, v191
	ds_write_b32 v103, v127 offset:816
	ds_write_b32 v103, v135 offset:7616
	v_pk_fma_f32 v[210:211], v[150:151], v[188:189], v[210:211]
	s_waitcnt lgkmcnt(15)
; #define LAS __attribute__((address_space(3)))
; __device__ __forceinline__ unsigned pk2(float lo, float hi) { f32x2 v = {lo, hi}; nbf2 r = __builtin_convertvector(v, nbf2); return __builtin_bit_cast(unsigned, r); }
; __device__ __forceinline__ float bf_at(const u32x4& lo, const u32x4& hi, int r) { const unsigned w = (r < 8 ? lo : hi)[(r & 7) >> 1]; return (r & 1) ? bf_hi(w) : bf_lo(w); }
; __device__ __forceinline__ void s5_out_phase(LAS unsigned char* lds, const bf16_t* UZ, const unsigned char* ws, const float* dskip, bf16_t* YG) {
;     ...
;             for (int rr = 0; rr < 16; ++rr) {
;                 const int r = rr, rb = 15 - rr;
;                 { const f32x2 bb = {bf_at(fre0, fre1, r), bf_at(fim0, fim1, r)};
;                   const f32x2 n2 = cmac((f32x2){xfr, xfi}, (f32x2){ap[0].x, ap[0].x}, (f32x2){-ap[0].y, ap[0].y}, bb); xfr = n2.x; xfi = n2.y;
;                   *(LAS unsigned*)(xf + r * XB_PITCH + lane * 4) = pk2(n2.x, n2.y); }
;                 { const f32x2 bb = {bf_at(bre0, bre1, rb), bf_at(bim0, bim1, rb)};
;                   const f32x2 n2 = cmac((f32x2){xbr, xbi}, (f32x2){ap[1].x, ap[1].x}, (f32x2){-ap[1].y, ap[1].y}, bb); xbr = n2.x; xbi = n2.y;
;                   *(LAS unsigned*)(xbk + rb * XB_PITCH + lane * 4) = pk2(n2.x, n2.y); }
;             }
	v_pk_fma_f32 v[216:217], v[152:153], v[190:191], v[216:217]
	v_pk_fma_f32 v[188:189], v[16:17], v[188:189], v[210:211] op_sel:[0,1,0] op_sel_hi:[1,0,1]
	v_pk_fma_f32 v[190:191], v[36:37], v[190:191], v[216:217] op_sel:[0,1,0] op_sel_hi:[1,0,1]
	v_cvt_pk_bf16_f32 v114, v188, v189
	v_cvt_pk_bf16_f32 v128, v190, v191
	ds_write_b32 v103, v114 offset:1088
	ds_write_b32 v103, v128 offset:7344
	v_pk_fma_f32 v[212:213], v[150:151], v[188:189], v[212:213]
	v_pk_fma_f32 v[214:215], v[152:153], v[190:191], v[214:215]
	v_pk_fma_f32 v[188:189], v[16:17], v[188:189], v[212:213] op_sel:[0,1,0] op_sel_hi:[1,0,1]
	v_pk_fma_f32 v[190:191], v[36:37], v[190:191], v[214:215] op_sel:[0,1,0] op_sel_hi:[1,0,1]
	v_cvt_pk_bf16_f32 v119, v188, v189
	v_cvt_pk_bf16_f32 v131, v190, v191
	ds_write_b32 v103, v119 offset:1360
	ds_write_b32 v103, v131 offset:7072
	v_pk_fma_f32 v[218:219], v[150:151], v[188:189], v[218:219]
	v_pk_fma_f32 v[224:225], v[152:153], v[190:191], v[224:225]
	v_pk_fma_f32 v[188:189], v[16:17], v[188:189], v[218:219] op_sel:[0,1,0] op_sel_hi:[1,0,1]
	v_pk_fma_f32 v[190:191], v[36:37], v[190:191], v[224:225] op_sel:[0,1,0] op_sel_hi:[1,0,1]
	v_cvt_pk_bf16_f32 v121, v188, v189
	v_cvt_pk_bf16_f32 v132, v190, v191
	ds_write_b32 v103, v121 offset:1632
	ds_write_b32 v103, v132 offset:6800
	v_pk_fma_f32 v[220:221], v[150:151], v[188:189], v[220:221]
	v_pk_fma_f32 v[222:223], v[152:153], v[190:191], v[222:223]
	v_pk_fma_f32 v[188:189], v[16:17], v[188:189], v[220:221] op_sel:[0,1,0] op_sel_hi:[1,0,1]
	v_pk_fma_f32 v[190:191], v[36:37], v[190:191], v[222:223] op_sel:[0,1,0] op_sel_hi:[1,0,1]
	v_cvt_pk_bf16_f32 v127, v188, v189
	v_cvt_pk_bf16_f32 v135, v190, v191
	ds_write_b32 v103, v127 offset:1904
	ds_write_b32 v103, v135 offset:6528
	v_pk_fma_f32 v[226:227], v[150:151], v[188:189], v[226:227]
	s_waitcnt lgkmcnt(15)
	v_pk_fma_f32 v[232:233], v[152:153], v[190:191], v[232:233]
	v_pk_fma_f32 v[188:189], v[16:17], v[188:189], v[226:227] op_sel:[0,1,0] op_sel_hi:[1,0,1]
	v_pk_fma_f32 v[190:191], v[36:37], v[190:191], v[232:233] op_sel:[0,1,0] op_sel_hi:[1,0,1]
	v_cvt_pk_bf16_f32 v114, v188, v189
	v_cvt_pk_bf16_f32 v128, v190, v191
	ds_write_b32 v103, v114 offset:2176
	ds_write_b32 v103, v128 offset:6256
	v_pk_fma_f32 v[228:229], v[150:151], v[188:189], v[228:229]
	v_pk_fma_f32 v[230:231], v[152:153], v[190:191], v[230:231]
	v_pk_fma_f32 v[188:189], v[16:17], v[188:189], v[228:229] op_sel:[0,1,0] op_sel_hi:[1,0,1]
	v_pk_fma_f32 v[190:191], v[36:37], v[190:191], v[230:231] op_sel:[0,1,0] op_sel_hi:[1,0,1]
	v_cvt_pk_bf16_f32 v119, v188, v189
	v_cvt_pk_bf16_f32 v131, v190, v191
	ds_write_b32 v103, v119 offset:2448
	ds_write_b32 v103, v131 offset:5984
	v_pk_fma_f32 v[234:235], v[150:151], v[188:189], v[234:235]
	v_pk_fma_f32 v[240:241], v[152:153], v[190:191], v[240:241]
	v_pk_fma_f32 v[188:189], v[16:17], v[188:189], v[234:235] op_sel:[0,1,0] op_sel_hi:[1,0,1]
	v_pk_fma_f32 v[190:191], v[36:37], v[190:191], v[240:241] op_sel:[0,1,0] op_sel_hi:[1,0,1]
	v_cvt_pk_bf16_f32 v121, v188, v189
	v_cvt_pk_bf16_f32 v132, v190, v191
	ds_write_b32 v103, v121 offset:2720
	ds_write_b32 v103, v132 offset:5712
	v_pk_fma_f32 v[236:237], v[150:151], v[188:189], v[236:237]
	v_pk_fma_f32 v[238:239], v[152:153], v[190:191], v[238:239]
	v_pk_fma_f32 v[188:189], v[16:17], v[188:189], v[236:237] op_sel:[0,1,0] op_sel_hi:[1,0,1]
	v_pk_fma_f32 v[190:191], v[36:37], v[190:191], v[238:239] op_sel:[0,1,0] op_sel_hi:[1,0,1]
	v_cvt_pk_bf16_f32 v127, v188, v189
	v_cvt_pk_bf16_f32 v135, v190, v191
	ds_write_b32 v103, v127 offset:2992
	ds_write_b32 v103, v135 offset:5440
	v_pk_fma_f32 v[242:243], v[150:151], v[188:189], v[242:243]
	v_pk_fma_f32 v[248:249], v[152:153], v[190:191], v[248:249]
	v_pk_fma_f32 v[188:189], v[16:17], v[188:189], v[242:243] op_sel:[0,1,0] op_sel_hi:[1,0,1]
	v_pk_fma_f32 v[190:191], v[36:37], v[190:191], v[248:249] op_sel:[0,1,0] op_sel_hi:[1,0,1]
	v_cvt_pk_bf16_f32 v114, v188, v189
	v_cvt_pk_bf16_f32 v128, v190, v191
	ds_write_b32 v103, v114 offset:3264
	ds_write_b32 v103, v128 offset:5168
	v_pk_fma_f32 v[244:245], v[150:151], v[188:189], v[244:245]
	v_pk_fma_f32 v[246:247], v[152:153], v[190:191], v[246:247]
	v_pk_fma_f32 v[188:189], v[16:17], v[188:189], v[244:245] op_sel:[0,1,0] op_sel_hi:[1,0,1]
	v_pk_fma_f32 v[190:191], v[36:37], v[190:191], v[246:247] op_sel:[0,1,0] op_sel_hi:[1,0,1]
	v_cvt_pk_bf16_f32 v119, v188, v189
	v_cvt_pk_bf16_f32 v131, v190, v191
	ds_write_b32 v103, v119 offset:3536
	ds_write_b32 v103, v131 offset:4896
	v_pk_fma_f32 v[250:251], v[150:151], v[188:189], v[250:251]
	s_waitcnt lgkmcnt(15)
; __device__ __forceinline__ void s5_out_phase(LAS unsigned char* lds, const bf16_t* UZ, const unsigned char* ws, const float* dskip, bf16_t* YG) {
;     ...
;             for (int nt = 0; nt < 8; ++nt) {
;                 const f32x4 z = {0.f, 0.f, 0.f, 0.f};
;                 const f32x4 cf = __builtin_amdgcn_mfma_f32_16x16x16bf16_1k(Uf[mf], Bf[0][nt], z, 0, 0, 0);
;                 const f32x4 cb = __builtin_amdgcn_mfma_f32_16x16x16bf16_1k(Uf[mb], Bf[1][nt], z, 0, 0, 0);
;                 u32x2 wf, wb; wf.x = pk2(cf[0], cf[1]); wf.y = pk2(cf[2], cf[3]); wb.x = pk2(cb[0], cb[1]); wb.y = pk2(cb[2], cb[3]);
;                 *(LAS u32x2*)(wl + nt * 640 + wofs) = wf;
;                 *(LAS u32x2*)(wl + BUT_BYTES + nt * 640 + wofs) = wb;
;             }
;             WAVE_LDS_FENCE();
;             const LAS unsigned char* rp = wl + lane * 80;
;             const u32x4 fre0 = *(const LAS u32x4*)(rp), fre1 = *(const LAS u32x4*)(rp + 16), fim0 = *(const LAS u32x4*)(rp + 32), fim1 = *(const LAS u32x4*)(rp + 48);
;             const u32x4 bre0 = *(const LAS u32x4*)(rp + BUT_BYTES), bre1 = *(const LAS u32x4*)(rp + BUT_BYTES + 16), bim0 = *(const LAS u32x4*)(rp + BUT_BYTES + 32), bim1 = *(const LAS u32x4*)(rp + BUT_BYTES + 48);
;             LAS unsigned char* xf = wl + 2 * BUT_BYTES; LAS unsigned char* xbk = xf + XB_BYTES;
; #pragma unroll
;             for (int rr = 0; rr < 16; ++rr) {
;                 const int r = rr, rb = 15 - rr;
;                 { const f32x2 bb = {bf_at(fre0, fre1, r), bf_at(fim0, fim1, r)};
;                   const f32x2 n2 = cmac((f32x2){xfr, xfi}, (f32x2){ap[0].x, ap[0].x}, (f32x2){-ap[0].y, ap[0].y}, bb); xfr = n2.x; xfi = n2.y;
;                   *(LAS unsigned*)(xf + r * XB_PITCH + lane * 4) = pk2(n2.x, n2.y); }
;                 { const f32x2 bb = {bf_at(bre0, bre1, rb), bf_at(bim0, bim1, rb)};
;                   const f32x2 n2 = cmac((f32x2){xbr, xbi}, (f32x2){ap[1].x, ap[1].x}, (f32x2){-ap[1].y, ap[1].y}, bb); xbr = n2.x; xbi = n2.y;
;                   *(LAS unsigned*)(xbk + rb * XB_PITCH + lane * 4) = pk2(n2.x, n2.y); }
;             }
;             WAVE_LDS_FENCE();
; #pragma unroll
;             for (int ks = 0; ks < 4; ++ks) {
;                 const bf16x8 Xf = *(const LAS bf16x8*)(xf + fr * XB_PITCH + (8 * fq + 32 * ks) * 2);
;                 const bf16x8 Xb = *(const LAS bf16x8*)(xbk + fr * XB_PITCH + (8 * fq + 32 * ks) * 2);
	v_pk_fma_f32 v[196:197], v[152:153], v[190:191], v[196:197]
	v_pk_fma_f32 v[188:189], v[16:17], v[188:189], v[250:251] op_sel:[0,1,0] op_sel_hi:[1,0,1]
	v_pk_fma_f32 v[190:191], v[36:37], v[190:191], v[196:197] op_sel:[0,1,0] op_sel_hi:[1,0,1]
	v_cvt_pk_bf16_f32 v121, v188, v189
	v_cvt_pk_bf16_f32 v132, v190, v191
	ds_write_b32 v103, v121 offset:3808
	ds_write_b32 v103, v132 offset:4624
	v_pk_fma_f32 v[252:253], v[150:151], v[188:189], v[252:253]
	v_pk_fma_f32 v[194:195], v[152:153], v[190:191], v[194:195]
	v_pk_fma_f32 v[188:189], v[16:17], v[188:189], v[252:253] op_sel:[0,1,0] op_sel_hi:[1,0,1]
	v_pk_fma_f32 v[190:191], v[36:37], v[190:191], v[194:195] op_sel:[0,1,0] op_sel_hi:[1,0,1]
	v_cvt_pk_bf16_f32 v127, v188, v189
	v_cvt_pk_bf16_f32 v135, v190, v191
	ds_write_b32 v103, v127 offset:4080
	ds_write_b32 v103, v135 offset:4352
	ds_read_b128 v[194:197], v110
	ds_read_b128 v[198:201], v110 offset:64
	ds_read_b128 v[202:205], v110 offset:128
	ds_read_b128 v[206:209], v110 offset:192
	ds_read_b128 v[210:213], v110 offset:4352
	ds_read_b128 v[214:217], v110 offset:4416
	ds_read_b128 v[218:221], v110 offset:4480
	ds_read_b128 v[222:225], v110 offset:4544
	v_mfma_f32_16x16x16_bf16 v[226:229], v[60:61], v[170:171], 0
	v_mfma_f32_16x16x16_bf16 v[230:233], v[76:77], v[168:169], 0
	v_mfma_f32_16x16x16_bf16 v[234:237], v[62:63], v[170:171], 0
	v_mfma_f32_16x16x16_bf16 v[238:241], v[78:79], v[168:169], 0
	s_nop 4
	ds_write_b64 v136, v[226:227]
	s_nop 2
	ds_write_b64 v136, v[228:229] offset:144
	v_mfma_f32_16x16x16_bf16 v[242:245], v[64:65], v[170:171], 0
	s_nop 0
	ds_write_b64 v136, v[230:231] offset:9216
	ds_write_b64 v136, v[232:233] offset:9360
	v_mfma_f32_16x16x16_bf16 v[246:249], v[80:81], v[168:169], 0
	ds_write_b64 v136, v[234:235] offset:1152
	ds_write_b64 v136, v[236:237] offset:1296
	v_mfma_f32_16x16x16_bf16 v[226:229], v[66:67], v[170:171], 0
	ds_write_b64 v136, v[238:239] offset:10368
	ds_write_b64 v136, v[240:241] offset:10512
	v_mfma_f32_16x16x16_bf16 v[230:233], v[82:83], v[168:169], 0
	ds_write_b64 v136, v[242:243] offset:2304
	ds_write_b64 v136, v[244:245] offset:2448
	v_mfma_f32_16x16x16_bf16 v[234:237], v[68:69], v[170:171], 0
	ds_write_b64 v136, v[246:247] offset:11520
	ds_write_b64 v136, v[248:249] offset:11664
	v_mfma_f32_16x16x16_bf16 v[238:241], v[84:85], v[168:169], 0
	ds_write_b64 v136, v[226:227] offset:3456
	ds_write_b64 v136, v[228:229] offset:3600
	v_mfma_f32_16x16x16_bf16 v[242:245], v[70:71], v[170:171], 0
	ds_write_b64 v136, v[230:231] offset:12672
	ds_write_b64 v136, v[232:233] offset:12816
	v_mfma_f32_16x16x16_bf16 v[246:249], v[86:87], v[168:169], 0
	ds_write_b64 v136, v[234:235] offset:4608
	ds_write_b64 v136, v[236:237] offset:4752
	v_mfma_f32_16x16x16_bf16 v[226:229], v[72:73], v[170:171], 0
	ds_write_b64 v136, v[238:239] offset:13824
	ds_write_b64 v136, v[240:241] offset:13968
	v_mfma_f32_16x16x16_bf16 v[230:233], v[88:89], v[168:169], 0
	ds_write_b64 v136, v[242:243] offset:5760
	ds_write_b64 v136, v[244:245] offset:5904
	v_mfma_f32_16x16x16_bf16 v[234:237], v[74:75], v[170:171], 0
	ds_write_b64 v136, v[246:247] offset:14976
	ds_write_b64 v136, v[248:249] offset:15120
	v_mfma_f32_16x16x16_bf16 v[238:241], v[90:91], v[168:169], 0
	ds_write_b64 v136, v[226:227] offset:6912
	ds_write_b64 v136, v[228:229] offset:7056
	ds_write_b64 v136, v[230:231] offset:16128
	ds_write_b64 v136, v[232:233] offset:16272
	s_nop 0
	ds_write_b64 v136, v[234:235] offset:8064
	ds_write_b64 v136, v[236:237] offset:8208
	s_nop 0
	ds_write_b64 v136, v[238:239] offset:17280
	ds_write_b64 v136, v[240:241] offset:17424
	s_waitcnt lgkmcnt(15)
	v_mfma_f32_16x16x32_bf16 v[48:51], v[0:3], v[194:197], 0
	v_mfma_f32_16x16x32_bf16 v[44:47], v[20:23], v[210:213], 0
	v_mfma_f32_16x16x32_bf16 v[48:51], v[4:7], v[198:201], v[48:51]
	v_mfma_f32_16x16x32_bf16 v[44:47], v[24:27], v[214:217], v[44:47]
	v_mfma_f32_16x16x32_bf16 v[48:51], v[8:11], v[202:205], v[48:51]
	v_mfma_f32_16x16x32_bf16 v[44:47], v[28:31], v[218:221], v[44:47]
	v_mfma_f32_16x16x32_bf16 v[48:51], v[12:15], v[206:209], v[48:51]
	v_mfma_f32_16x16x32_bf16 v[44:47], v[32:35], v[222:225], v[44:47]
	ds_read_b128 v[194:197], v139
	ds_read_b128 v[198:201], v139 offset:9328
	ds_read_b128 v[202:205], v139 offset:16
	ds_read_b128 v[206:209], v139 offset:9312
	ds_read_b128 v[210:213], v139 offset:32
	ds_read_b128 v[214:217], v139 offset:9296
	ds_read_b128 v[218:221], v139 offset:48
	ds_read_b128 v[222:225], v139 offset:9280
	ds_read_b128 v[226:229], v139 offset:64
	ds_read_b128 v[230:233], v139 offset:9264
	ds_read_b128 v[234:237], v139 offset:80
	ds_read_b128 v[238:241], v139 offset:9248
	ds_read_b128 v[242:245], v139 offset:96
	ds_read_b128 v[246:249], v139 offset:9232
	ds_read_b128 v[250:253], v139 offset:112
	s_waitcnt lgkmcnt(14)
	v_pk_fma_f32 v[194:195], v[150:151], v[188:189], v[194:195]
	s_waitcnt lgkmcnt(13)
	v_pk_fma_f32 v[200:201], v[152:153], v[190:191], v[200:201]
	v_pk_fma_f32 v[188:189], v[16:17], v[188:189], v[194:195] op_sel:[0,1,0] op_sel_hi:[1,0,1]
	v_pk_fma_f32 v[190:191], v[36:37], v[190:191], v[200:201] op_sel:[0,1,0] op_sel_hi:[1,0,1]
	v_cvt_pk_bf16_f32 v114, v188, v189
	v_cvt_pk_bf16_f32 v128, v190, v191
	ds_write_b32 v103, v114
	ds_write_b32 v103, v128 offset:8432
	v_pk_fma_f32 v[196:197], v[150:151], v[188:189], v[196:197]
	v_pk_fma_f32 v[198:199], v[152:153], v[190:191], v[198:199]
	v_pk_fma_f32 v[188:189], v[16:17], v[188:189], v[196:197] op_sel:[0,1,0] op_sel_hi:[1,0,1]
	v_pk_fma_f32 v[190:191], v[36:37], v[190:191], v[198:199] op_sel:[0,1,0] op_sel_hi:[1,0,1]
	v_cvt_pk_bf16_f32 v119, v188, v189
	v_cvt_pk_bf16_f32 v131, v190, v191
	ds_write_b32 v103, v119 offset:272
	ds_write_b32 v103, v131 offset:8160
	ds_read_b128 v[194:197], v139 offset:9216
	s_waitcnt lgkmcnt(15)
; #define LAS __attribute__((address_space(3)))
; __device__ __forceinline__ unsigned pk2(float lo, float hi) { f32x2 v = {lo, hi}; nbf2 r = __builtin_convertvector(v, nbf2); return __builtin_bit_cast(unsigned, r); }
; __device__ __forceinline__ float bf_at(const u32x4& lo, const u32x4& hi, int r) { const unsigned w = (r < 8 ? lo : hi)[(r & 7) >> 1]; return (r & 1) ? bf_hi(w) : bf_lo(w); }
; __device__ __forceinline__ void s5_out_phase(LAS unsigned char* lds, const bf16_t* UZ, const unsigned char* ws, const float* dskip, bf16_t* YG) {
;     ...
;             for (int rr = 0; rr < 16; ++rr) {
;                 const int r = rr, rb = 15 - rr;
;                 { const f32x2 bb = {bf_at(fre0, fre1, r), bf_at(fim0, fim1, r)};
;                   const f32x2 n2 = cmac((f32x2){xfr, xfi}, (f32x2){ap[0].x, ap[0].x}, (f32x2){-ap[0].y, ap[0].y}, bb); xfr = n2.x; xfi = n2.y;
;                   *(LAS unsigned*)(xf + r * XB_PITCH + lane * 4) = pk2(n2.x, n2.y); }
;                 { const f32x2 bb = {bf_at(bre0, bre1, rb), bf_at(bim0, bim1, rb)};
;                   const f32x2 n2 = cmac((f32x2){xbr, xbi}, (f32x2){ap[1].x, ap[1].x}, (f32x2){-ap[1].y, ap[1].y}, bb); xbr = n2.x; xbi = n2.y;
;                   *(LAS unsigned*)(xbk + rb * XB_PITCH + lane * 4) = pk2(n2.x, n2.y); }
;             }
	v_pk_fma_f32 v[202:203], v[150:151], v[188:189], v[202:203]
	v_pk_fma_f32 v[208:209], v[152:153], v[190:191], v[208:209]
	v_pk_fma_f32 v[188:189], v[16:17], v[188:189], v[202:203] op_sel:[0,1,0] op_sel_hi:[1,0,1]
	v_pk_fma_f32 v[190:191], v[36:37], v[190:191], v[208:209] op_sel:[0,1,0] op_sel_hi:[1,0,1]
	v_cvt_pk_bf16_f32 v121, v188, v189
	v_cvt_pk_bf16_f32 v132, v190, v191
	ds_write_b32 v103, v121 offset:544
	ds_write_b32 v103, v132 offset:7888
	v_pk_fma_f32 v[204:205], v[150:151], v[188:189], v[204:205]
	v_pk_fma_f32 v[206:207], v[152:153], v[190:191], v[206:207]
	v_pk_fma_f32 v[188:189], v[16:17], v[188:189], v[204:205] op_sel:[0,1,0] op_sel_hi:[1,0,1]
	v_pk_fma_f32 v[190:191], v[36:37], v[190:191], v[206:207] op_sel:[0,1,0] op_sel_hi:[1,0,1]
	v_cvt_pk_bf16_f32 v127, v188, v189
	v_cvt_pk_bf16_f32 v135, v190, v191
	ds_write_b32 v103, v127 offset:816
	ds_write_b32 v103, v135 offset:7616
	v_pk_fma_f32 v[210:211], v[150:151], v[188:189], v[210:211]
	s_waitcnt lgkmcnt(15)
	v_pk_fma_f32 v[216:217], v[152:153], v[190:191], v[216:217]
	v_pk_fma_f32 v[188:189], v[16:17], v[188:189], v[210:211] op_sel:[0,1,0] op_sel_hi:[1,0,1]
	v_pk_fma_f32 v[190:191], v[36:37], v[190:191], v[216:217] op_sel:[0,1,0] op_sel_hi:[1,0,1]
	v_cvt_pk_bf16_f32 v114, v188, v189
	v_cvt_pk_bf16_f32 v128, v190, v191
	ds_write_b32 v103, v114 offset:1088
	ds_write_b32 v103, v128 offset:7344
	v_pk_fma_f32 v[212:213], v[150:151], v[188:189], v[212:213]
	v_pk_fma_f32 v[214:215], v[152:153], v[190:191], v[214:215]
	v_pk_fma_f32 v[188:189], v[16:17], v[188:189], v[212:213] op_sel:[0,1,0] op_sel_hi:[1,0,1]
	v_pk_fma_f32 v[190:191], v[36:37], v[190:191], v[214:215] op_sel:[0,1,0] op_sel_hi:[1,0,1]
	v_cvt_pk_bf16_f32 v119, v188, v189
	v_cvt_pk_bf16_f32 v131, v190, v191
	ds_write_b32 v103, v119 offset:1360
	ds_write_b32 v103, v131 offset:7072
	v_pk_fma_f32 v[218:219], v[150:151], v[188:189], v[218:219]
	v_pk_fma_f32 v[224:225], v[152:153], v[190:191], v[224:225]
	v_pk_fma_f32 v[188:189], v[16:17], v[188:189], v[218:219] op_sel:[0,1,0] op_sel_hi:[1,0,1]
	v_pk_fma_f32 v[190:191], v[36:37], v[190:191], v[224:225] op_sel:[0,1,0] op_sel_hi:[1,0,1]
	v_cvt_pk_bf16_f32 v121, v188, v189
	v_cvt_pk_bf16_f32 v132, v190, v191
	ds_write_b32 v103, v121 offset:1632
	ds_write_b32 v103, v132 offset:6800
	v_pk_fma_f32 v[220:221], v[150:151], v[188:189], v[220:221]
	v_pk_fma_f32 v[222:223], v[152:153], v[190:191], v[222:223]
	v_pk_fma_f32 v[188:189], v[16:17], v[188:189], v[220:221] op_sel:[0,1,0] op_sel_hi:[1,0,1]
	v_pk_fma_f32 v[190:191], v[36:37], v[190:191], v[222:223] op_sel:[0,1,0] op_sel_hi:[1,0,1]
	v_cvt_pk_bf16_f32 v127, v188, v189
	v_cvt_pk_bf16_f32 v135, v190, v191
	ds_write_b32 v103, v127 offset:1904
	ds_write_b32 v103, v135 offset:6528
	v_pk_fma_f32 v[226:227], v[150:151], v[188:189], v[226:227]
	s_waitcnt lgkmcnt(15)
	v_pk_fma_f32 v[232:233], v[152:153], v[190:191], v[232:233]
	v_pk_fma_f32 v[188:189], v[16:17], v[188:189], v[226:227] op_sel:[0,1,0] op_sel_hi:[1,0,1]
	v_pk_fma_f32 v[190:191], v[36:37], v[190:191], v[232:233] op_sel:[0,1,0] op_sel_hi:[1,0,1]
	v_cvt_pk_bf16_f32 v114, v188, v189
	v_cvt_pk_bf16_f32 v128, v190, v191
	ds_write_b32 v103, v114 offset:2176
	ds_write_b32 v103, v128 offset:6256
	v_pk_fma_f32 v[228:229], v[150:151], v[188:189], v[228:229]
	v_pk_fma_f32 v[230:231], v[152:153], v[190:191], v[230:231]
	v_pk_fma_f32 v[188:189], v[16:17], v[188:189], v[228:229] op_sel:[0,1,0] op_sel_hi:[1,0,1]
	v_pk_fma_f32 v[190:191], v[36:37], v[190:191], v[230:231] op_sel:[0,1,0] op_sel_hi:[1,0,1]
	v_cvt_pk_bf16_f32 v119, v188, v189
	v_cvt_pk_bf16_f32 v131, v190, v191
	ds_write_b32 v103, v119 offset:2448
	ds_write_b32 v103, v131 offset:5984
	v_pk_fma_f32 v[234:235], v[150:151], v[188:189], v[234:235]
	v_pk_fma_f32 v[240:241], v[152:153], v[190:191], v[240:241]
	v_pk_fma_f32 v[188:189], v[16:17], v[188:189], v[234:235] op_sel:[0,1,0] op_sel_hi:[1,0,1]
	v_pk_fma_f32 v[190:191], v[36:37], v[190:191], v[240:241] op_sel:[0,1,0] op_sel_hi:[1,0,1]
	v_cvt_pk_bf16_f32 v121, v188, v189
	v_cvt_pk_bf16_f32 v132, v190, v191
	ds_write_b32 v103, v121 offset:2720
	ds_write_b32 v103, v132 offset:5712
	v_pk_fma_f32 v[236:237], v[150:151], v[188:189], v[236:237]
	v_pk_fma_f32 v[238:239], v[152:153], v[190:191], v[238:239]
	v_pk_fma_f32 v[188:189], v[16:17], v[188:189], v[236:237] op_sel:[0,1,0] op_sel_hi:[1,0,1]
	v_pk_fma_f32 v[190:191], v[36:37], v[190:191], v[238:239] op_sel:[0,1,0] op_sel_hi:[1,0,1]
	v_cvt_pk_bf16_f32 v127, v188, v189
	v_cvt_pk_bf16_f32 v135, v190, v191
	ds_write_b32 v103, v127 offset:2992
	ds_write_b32 v103, v135 offset:5440
	v_pk_fma_f32 v[242:243], v[150:151], v[188:189], v[242:243]
	v_pk_fma_f32 v[248:249], v[152:153], v[190:191], v[248:249]
	v_pk_fma_f32 v[188:189], v[16:17], v[188:189], v[242:243] op_sel:[0,1,0] op_sel_hi:[1,0,1]
	v_pk_fma_f32 v[190:191], v[36:37], v[190:191], v[248:249] op_sel:[0,1,0] op_sel_hi:[1,0,1]
	v_cvt_pk_bf16_f32 v114, v188, v189
	v_cvt_pk_bf16_f32 v128, v190, v191
	ds_write_b32 v103, v114 offset:3264
	ds_write_b32 v103, v128 offset:5168
	v_pk_fma_f32 v[244:245], v[150:151], v[188:189], v[244:245]
	v_pk_fma_f32 v[246:247], v[152:153], v[190:191], v[246:247]
	v_pk_fma_f32 v[188:189], v[16:17], v[188:189], v[244:245] op_sel:[0,1,0] op_sel_hi:[1,0,1]
	v_pk_fma_f32 v[190:191], v[36:37], v[190:191], v[246:247] op_sel:[0,1,0] op_sel_hi:[1,0,1]
	v_cvt_pk_bf16_f32 v119, v188, v189
	v_cvt_pk_bf16_f32 v131, v190, v191
	ds_write_b32 v103, v119 offset:3536
	ds_write_b32 v103, v131 offset:4896
	v_pk_fma_f32 v[250:251], v[150:151], v[188:189], v[250:251]
	s_waitcnt lgkmcnt(15)
; __device__ __forceinline__ void s5_out_phase(LAS unsigned char* lds, const bf16_t* UZ, const unsigned char* ws, const float* dskip, bf16_t* YG) {
;     ...
;             for (int nt = 0; nt < 8; ++nt) {
;                 const f32x4 z = {0.f, 0.f, 0.f, 0.f};
;                 const f32x4 cf = __builtin_amdgcn_mfma_f32_16x16x16bf16_1k(Uf[mf], Bf[0][nt], z, 0, 0, 0);
;                 const f32x4 cb = __builtin_amdgcn_mfma_f32_16x16x16bf16_1k(Uf[mb], Bf[1][nt], z, 0, 0, 0);
;                 u32x2 wf, wb; wf.x = pk2(cf[0], cf[1]); wf.y = pk2(cf[2], cf[3]); wb.x = pk2(cb[0], cb[1]); wb.y = pk2(cb[2], cb[3]);
;                 *(LAS u32x2*)(wl + nt * 640 + wofs) = wf;
;                 *(LAS u32x2*)(wl + BUT_BYTES + nt * 640 + wofs) = wb;
;             }
;             WAVE_LDS_FENCE();
;             const LAS unsigned char* rp = wl + lane * 80;
;             const u32x4 fre0 = *(const LAS u32x4*)(rp), fre1 = *(const LAS u32x4*)(rp + 16), fim0 = *(const LAS u32x4*)(rp + 32), fim1 = *(const LAS u32x4*)(rp + 48);
;             const u32x4 bre0 = *(const LAS u32x4*)(rp + BUT_BYTES), bre1 = *(const LAS u32x4*)(rp + BUT_BYTES + 16), bim0 = *(const LAS u32x4*)(rp + BUT_BYTES + 32), bim1 = *(const LAS u32x4*)(rp + BUT_BYTES + 48);
;             LAS unsigned char* xf = wl + 2 * BUT_BYTES; LAS unsigned char* xbk = xf + XB_BYTES;
; #pragma unroll
;             for (int rr = 0; rr < 16; ++rr) {
;                 const int r = rr, rb = 15 - rr;
;                 { const f32x2 bb = {bf_at(fre0, fre1, r), bf_at(fim0, fim1, r)};
;                   const f32x2 n2 = cmac((f32x2){xfr, xfi}, (f32x2){ap[0].x, ap[0].x}, (f32x2){-ap[0].y, ap[0].y}, bb); xfr = n2.x; xfi = n2.y;
;                   *(LAS unsigned*)(xf + r * XB_PITCH + lane * 4) = pk2(n2.x, n2.y); }
;                 { const f32x2 bb = {bf_at(bre0, bre1, rb), bf_at(bim0, bim1, rb)};
;                   const f32x2 n2 = cmac((f32x2){xbr, xbi}, (f32x2){ap[1].x, ap[1].x}, (f32x2){-ap[1].y, ap[1].y}, bb); xbr = n2.x; xbi = n2.y;
;                   *(LAS unsigned*)(xbk + rb * XB_PITCH + lane * 4) = pk2(n2.x, n2.y); }
;             }
;             WAVE_LDS_FENCE();
; #pragma unroll
;             for (int ks = 0; ks < 4; ++ks) {
;                 const bf16x8 Xf = *(const LAS bf16x8*)(xf + fr * XB_PITCH + (8 * fq + 32 * ks) * 2);
;                 const bf16x8 Xb = *(const LAS bf16x8*)(xbk + fr * XB_PITCH + (8 * fq + 32 * ks) * 2);
	v_pk_fma_f32 v[196:197], v[152:153], v[190:191], v[196:197]
	v_pk_fma_f32 v[188:189], v[16:17], v[188:189], v[250:251] op_sel:[0,1,0] op_sel_hi:[1,0,1]
	v_pk_fma_f32 v[190:191], v[36:37], v[190:191], v[196:197] op_sel:[0,1,0] op_sel_hi:[1,0,1]
	v_cvt_pk_bf16_f32 v121, v188, v189
	v_cvt_pk_bf16_f32 v132, v190, v191
	ds_write_b32 v103, v121 offset:3808
	ds_write_b32 v103, v132 offset:4624
	v_pk_fma_f32 v[252:253], v[150:151], v[188:189], v[252:253]
	v_pk_fma_f32 v[194:195], v[152:153], v[190:191], v[194:195]
	v_pk_fma_f32 v[188:189], v[16:17], v[188:189], v[252:253] op_sel:[0,1,0] op_sel_hi:[1,0,1]
	v_pk_fma_f32 v[190:191], v[36:37], v[190:191], v[194:195] op_sel:[0,1,0] op_sel_hi:[1,0,1]
	v_cvt_pk_bf16_f32 v127, v188, v189
	v_cvt_pk_bf16_f32 v135, v190, v191
	ds_write_b32 v103, v127 offset:4080
	ds_write_b32 v103, v135 offset:4352
	ds_read_b128 v[194:197], v110
	ds_read_b128 v[198:201], v110 offset:64
	ds_read_b128 v[202:205], v110 offset:128
	ds_read_b128 v[206:209], v110 offset:192
	ds_read_b128 v[210:213], v110 offset:4352
	ds_read_b128 v[214:217], v110 offset:4416
	ds_read_b128 v[218:221], v110 offset:4480
	ds_read_b128 v[222:225], v110 offset:4544
	v_mfma_f32_16x16x16_bf16 v[226:229], v[60:61], v[168:169], 0
	v_mfma_f32_16x16x16_bf16 v[230:233], v[76:77], v[170:171], 0
	v_mfma_f32_16x16x16_bf16 v[234:237], v[62:63], v[168:169], 0
	v_mfma_f32_16x16x16_bf16 v[238:241], v[78:79], v[170:171], 0
	s_nop 4
	ds_write_b64 v136, v[226:227]
	s_nop 2
	ds_write_b64 v136, v[228:229] offset:144
	v_mfma_f32_16x16x16_bf16 v[242:245], v[64:65], v[168:169], 0
	s_nop 0
	ds_write_b64 v136, v[230:231] offset:9216
	ds_write_b64 v136, v[232:233] offset:9360
	v_mfma_f32_16x16x16_bf16 v[246:249], v[80:81], v[170:171], 0
	ds_write_b64 v136, v[234:235] offset:1152
	ds_write_b64 v136, v[236:237] offset:1296
	v_mfma_f32_16x16x16_bf16 v[226:229], v[66:67], v[168:169], 0
	ds_write_b64 v136, v[238:239] offset:10368
	ds_write_b64 v136, v[240:241] offset:10512
	v_mfma_f32_16x16x16_bf16 v[230:233], v[82:83], v[170:171], 0
	ds_write_b64 v136, v[242:243] offset:2304
	ds_write_b64 v136, v[244:245] offset:2448
	v_mfma_f32_16x16x16_bf16 v[234:237], v[68:69], v[168:169], 0
	ds_write_b64 v136, v[246:247] offset:11520
	ds_write_b64 v136, v[248:249] offset:11664
	v_mfma_f32_16x16x16_bf16 v[238:241], v[84:85], v[170:171], 0
	ds_write_b64 v136, v[226:227] offset:3456
	ds_write_b64 v136, v[228:229] offset:3600
	v_mfma_f32_16x16x16_bf16 v[242:245], v[70:71], v[168:169], 0
	ds_write_b64 v136, v[230:231] offset:12672
	ds_write_b64 v136, v[232:233] offset:12816
	v_mfma_f32_16x16x16_bf16 v[246:249], v[86:87], v[170:171], 0
	ds_write_b64 v136, v[234:235] offset:4608
	ds_write_b64 v136, v[236:237] offset:4752
	v_mfma_f32_16x16x16_bf16 v[226:229], v[72:73], v[168:169], 0
	ds_write_b64 v136, v[238:239] offset:13824
	ds_write_b64 v136, v[240:241] offset:13968
	v_mfma_f32_16x16x16_bf16 v[230:233], v[88:89], v[170:171], 0
	ds_write_b64 v136, v[242:243] offset:5760
	ds_write_b64 v136, v[244:245] offset:5904
	v_mfma_f32_16x16x16_bf16 v[234:237], v[74:75], v[168:169], 0
	ds_write_b64 v136, v[246:247] offset:14976
	ds_write_b64 v136, v[248:249] offset:15120
	v_mfma_f32_16x16x16_bf16 v[238:241], v[90:91], v[170:171], 0
	ds_write_b64 v136, v[226:227] offset:6912
	ds_write_b64 v136, v[228:229] offset:7056
	ds_write_b64 v136, v[230:231] offset:16128
	ds_write_b64 v136, v[232:233] offset:16272
	s_nop 0
	ds_write_b64 v136, v[234:235] offset:8064
	ds_write_b64 v136, v[236:237] offset:8208
	s_nop 0
	ds_write_b64 v136, v[238:239] offset:17280
	ds_write_b64 v136, v[240:241] offset:17424
	s_waitcnt lgkmcnt(15)
	v_mfma_f32_16x16x32_bf16 v[56:59], v[0:3], v[194:197], 0
	v_mfma_f32_16x16x32_bf16 v[52:55], v[20:23], v[210:213], 0
	v_mfma_f32_16x16x32_bf16 v[56:59], v[4:7], v[198:201], v[56:59]
	v_mfma_f32_16x16x32_bf16 v[52:55], v[24:27], v[214:217], v[52:55]
	v_mfma_f32_16x16x32_bf16 v[56:59], v[8:11], v[202:205], v[56:59]
	v_mfma_f32_16x16x32_bf16 v[52:55], v[28:31], v[218:221], v[52:55]
	v_mfma_f32_16x16x32_bf16 v[56:59], v[12:15], v[206:209], v[56:59]
	v_mfma_f32_16x16x32_bf16 v[52:55], v[32:35], v[222:225], v[52:55]
	ds_read_b128 v[194:197], v139
	ds_read_b128 v[198:201], v139 offset:9328
	ds_read_b128 v[202:205], v139 offset:16
	ds_read_b128 v[206:209], v139 offset:9312
	ds_read_b128 v[210:213], v139 offset:32
	ds_read_b128 v[214:217], v139 offset:9296
	ds_read_b128 v[218:221], v139 offset:48
	ds_read_b128 v[222:225], v139 offset:9280
	ds_read_b128 v[226:229], v139 offset:64
	ds_read_b128 v[230:233], v139 offset:9264
	ds_read_b128 v[234:237], v139 offset:80
	ds_read_b128 v[238:241], v139 offset:9248
	ds_read_b128 v[242:245], v139 offset:96
	ds_read_b128 v[246:249], v139 offset:9232
	ds_read_b128 v[250:253], v139 offset:112
	s_waitcnt lgkmcnt(14)
	v_pk_fma_f32 v[194:195], v[150:151], v[188:189], v[194:195]
	s_waitcnt lgkmcnt(13)
	v_pk_fma_f32 v[200:201], v[152:153], v[190:191], v[200:201]
	v_pk_fma_f32 v[188:189], v[16:17], v[188:189], v[194:195] op_sel:[0,1,0] op_sel_hi:[1,0,1]
	v_pk_fma_f32 v[190:191], v[36:37], v[190:191], v[200:201] op_sel:[0,1,0] op_sel_hi:[1,0,1]
	v_cvt_pk_bf16_f32 v114, v188, v189
	v_cvt_pk_bf16_f32 v128, v190, v191
	ds_write_b32 v103, v114
	ds_write_b32 v103, v128 offset:8432
	v_pk_fma_f32 v[196:197], v[150:151], v[188:189], v[196:197]
	v_pk_fma_f32 v[198:199], v[152:153], v[190:191], v[198:199]
	v_pk_fma_f32 v[188:189], v[16:17], v[188:189], v[196:197] op_sel:[0,1,0] op_sel_hi:[1,0,1]
	v_pk_fma_f32 v[190:191], v[36:37], v[190:191], v[198:199] op_sel:[0,1,0] op_sel_hi:[1,0,1]
	v_cvt_pk_bf16_f32 v119, v188, v189
	v_cvt_pk_bf16_f32 v131, v190, v191
	ds_write_b32 v103, v119 offset:272
	ds_write_b32 v103, v131 offset:8160
	ds_read_b128 v[194:197], v139 offset:9216
	s_waitcnt lgkmcnt(15)
; #define LAS __attribute__((address_space(3)))
; __device__ __forceinline__ unsigned pk2(float lo, float hi) { f32x2 v = {lo, hi}; nbf2 r = __builtin_convertvector(v, nbf2); return __builtin_bit_cast(unsigned, r); }
; __device__ __forceinline__ float bf_at(const u32x4& lo, const u32x4& hi, int r) { const unsigned w = (r < 8 ? lo : hi)[(r & 7) >> 1]; return (r & 1) ? bf_hi(w) : bf_lo(w); }
; __device__ __forceinline__ void s5_out_phase(LAS unsigned char* lds, const bf16_t* UZ, const unsigned char* ws, const float* dskip, bf16_t* YG) {
;     ...
;             for (int rr = 0; rr < 16; ++rr) {
;                 const int r = rr, rb = 15 - rr;
;                 { const f32x2 bb = {bf_at(fre0, fre1, r), bf_at(fim0, fim1, r)};
;                   const f32x2 n2 = cmac((f32x2){xfr, xfi}, (f32x2){ap[0].x, ap[0].x}, (f32x2){-ap[0].y, ap[0].y}, bb); xfr = n2.x; xfi = n2.y;
;                   *(LAS unsigned*)(xf + r * XB_PITCH + lane * 4) = pk2(n2.x, n2.y); }
;                 { const f32x2 bb = {bf_at(bre0, bre1, rb), bf_at(bim0, bim1, rb)};
;                   const f32x2 n2 = cmac((f32x2){xbr, xbi}, (f32x2){ap[1].x, ap[1].x}, (f32x2){-ap[1].y, ap[1].y}, bb); xbr = n2.x; xbi = n2.y;
;                   *(LAS unsigned*)(xbk + rb * XB_PITCH + lane * 4) = pk2(n2.x, n2.y); }
;             }
	v_pk_fma_f32 v[202:203], v[150:151], v[188:189], v[202:203]
	v_pk_fma_f32 v[208:209], v[152:153], v[190:191], v[208:209]
	v_pk_fma_f32 v[188:189], v[16:17], v[188:189], v[202:203] op_sel:[0,1,0] op_sel_hi:[1,0,1]
	v_pk_fma_f32 v[190:191], v[36:37], v[190:191], v[208:209] op_sel:[0,1,0] op_sel_hi:[1,0,1]
	v_cvt_pk_bf16_f32 v121, v188, v189
	v_cvt_pk_bf16_f32 v132, v190, v191
	ds_write_b32 v103, v121 offset:544
	ds_write_b32 v103, v132 offset:7888
	v_pk_fma_f32 v[204:205], v[150:151], v[188:189], v[204:205]
	v_pk_fma_f32 v[206:207], v[152:153], v[190:191], v[206:207]
	v_pk_fma_f32 v[188:189], v[16:17], v[188:189], v[204:205] op_sel:[0,1,0] op_sel_hi:[1,0,1]
	v_pk_fma_f32 v[190:191], v[36:37], v[190:191], v[206:207] op_sel:[0,1,0] op_sel_hi:[1,0,1]
	v_cvt_pk_bf16_f32 v127, v188, v189
	v_cvt_pk_bf16_f32 v135, v190, v191
	ds_write_b32 v103, v127 offset:816
	ds_write_b32 v103, v135 offset:7616
	v_pk_fma_f32 v[210:211], v[150:151], v[188:189], v[210:211]
	s_waitcnt lgkmcnt(15)
	v_pk_fma_f32 v[216:217], v[152:153], v[190:191], v[216:217]
	v_pk_fma_f32 v[188:189], v[16:17], v[188:189], v[210:211] op_sel:[0,1,0] op_sel_hi:[1,0,1]
	v_pk_fma_f32 v[190:191], v[36:37], v[190:191], v[216:217] op_sel:[0,1,0] op_sel_hi:[1,0,1]
	v_cvt_pk_bf16_f32 v114, v188, v189
	v_cvt_pk_bf16_f32 v128, v190, v191
	ds_write_b32 v103, v114 offset:1088
	ds_write_b32 v103, v128 offset:7344
	v_pk_fma_f32 v[212:213], v[150:151], v[188:189], v[212:213]
	v_pk_fma_f32 v[214:215], v[152:153], v[190:191], v[214:215]
	v_pk_fma_f32 v[188:189], v[16:17], v[188:189], v[212:213] op_sel:[0,1,0] op_sel_hi:[1,0,1]
	v_pk_fma_f32 v[190:191], v[36:37], v[190:191], v[214:215] op_sel:[0,1,0] op_sel_hi:[1,0,1]
	v_cvt_pk_bf16_f32 v119, v188, v189
	v_cvt_pk_bf16_f32 v131, v190, v191
	ds_write_b32 v103, v119 offset:1360
	ds_write_b32 v103, v131 offset:7072
	v_pk_fma_f32 v[218:219], v[150:151], v[188:189], v[218:219]
	v_pk_fma_f32 v[224:225], v[152:153], v[190:191], v[224:225]
	v_pk_fma_f32 v[188:189], v[16:17], v[188:189], v[218:219] op_sel:[0,1,0] op_sel_hi:[1,0,1]
	v_pk_fma_f32 v[190:191], v[36:37], v[190:191], v[224:225] op_sel:[0,1,0] op_sel_hi:[1,0,1]
	v_cvt_pk_bf16_f32 v121, v188, v189
	v_cvt_pk_bf16_f32 v132, v190, v191
	ds_write_b32 v103, v121 offset:1632
	ds_write_b32 v103, v132 offset:6800
	v_pk_fma_f32 v[220:221], v[150:151], v[188:189], v[220:221]
	v_pk_fma_f32 v[222:223], v[152:153], v[190:191], v[222:223]
	v_pk_fma_f32 v[188:189], v[16:17], v[188:189], v[220:221] op_sel:[0,1,0] op_sel_hi:[1,0,1]
	v_pk_fma_f32 v[190:191], v[36:37], v[190:191], v[222:223] op_sel:[0,1,0] op_sel_hi:[1,0,1]
	v_cvt_pk_bf16_f32 v127, v188, v189
	v_cvt_pk_bf16_f32 v135, v190, v191
	ds_write_b32 v103, v127 offset:1904
	ds_write_b32 v103, v135 offset:6528
	v_pk_fma_f32 v[226:227], v[150:151], v[188:189], v[226:227]
	s_waitcnt lgkmcnt(15)
	v_pk_fma_f32 v[232:233], v[152:153], v[190:191], v[232:233]
	v_pk_fma_f32 v[188:189], v[16:17], v[188:189], v[226:227] op_sel:[0,1,0] op_sel_hi:[1,0,1]
	v_pk_fma_f32 v[190:191], v[36:37], v[190:191], v[232:233] op_sel:[0,1,0] op_sel_hi:[1,0,1]
	v_cvt_pk_bf16_f32 v114, v188, v189
	v_cvt_pk_bf16_f32 v128, v190, v191
	ds_write_b32 v103, v114 offset:2176
	ds_write_b32 v103, v128 offset:6256
	v_pk_fma_f32 v[228:229], v[150:151], v[188:189], v[228:229]
	v_pk_fma_f32 v[230:231], v[152:153], v[190:191], v[230:231]
	v_pk_fma_f32 v[188:189], v[16:17], v[188:189], v[228:229] op_sel:[0,1,0] op_sel_hi:[1,0,1]
	v_pk_fma_f32 v[190:191], v[36:37], v[190:191], v[230:231] op_sel:[0,1,0] op_sel_hi:[1,0,1]
	v_cvt_pk_bf16_f32 v119, v188, v189
	v_cvt_pk_bf16_f32 v131, v190, v191
	ds_write_b32 v103, v119 offset:2448
	ds_write_b32 v103, v131 offset:5984
	v_pk_fma_f32 v[234:235], v[150:151], v[188:189], v[234:235]
	v_pk_fma_f32 v[240:241], v[152:153], v[190:191], v[240:241]
	v_pk_fma_f32 v[188:189], v[16:17], v[188:189], v[234:235] op_sel:[0,1,0] op_sel_hi:[1,0,1]
	v_pk_fma_f32 v[190:191], v[36:37], v[190:191], v[240:241] op_sel:[0,1,0] op_sel_hi:[1,0,1]
	v_cvt_pk_bf16_f32 v121, v188, v189
	v_cvt_pk_bf16_f32 v132, v190, v191
	ds_write_b32 v103, v121 offset:2720
	ds_write_b32 v103, v132 offset:5712
	v_pk_fma_f32 v[236:237], v[150:151], v[188:189], v[236:237]
	v_pk_fma_f32 v[238:239], v[152:153], v[190:191], v[238:239]
	v_pk_fma_f32 v[188:189], v[16:17], v[188:189], v[236:237] op_sel:[0,1,0] op_sel_hi:[1,0,1]
	v_pk_fma_f32 v[190:191], v[36:37], v[190:191], v[238:239] op_sel:[0,1,0] op_sel_hi:[1,0,1]
	v_cvt_pk_bf16_f32 v127, v188, v189
	v_cvt_pk_bf16_f32 v135, v190, v191
	ds_write_b32 v103, v127 offset:2992
	ds_write_b32 v103, v135 offset:5440
	v_pk_fma_f32 v[242:243], v[150:151], v[188:189], v[242:243]
	v_pk_fma_f32 v[248:249], v[152:153], v[190:191], v[248:249]
	v_pk_fma_f32 v[188:189], v[16:17], v[188:189], v[242:243] op_sel:[0,1,0] op_sel_hi:[1,0,1]
	v_pk_fma_f32 v[190:191], v[36:37], v[190:191], v[248:249] op_sel:[0,1,0] op_sel_hi:[1,0,1]
	v_cvt_pk_bf16_f32 v114, v188, v189
	v_cvt_pk_bf16_f32 v128, v190, v191
	ds_write_b32 v103, v114 offset:3264
	ds_write_b32 v103, v128 offset:5168
	v_pk_fma_f32 v[244:245], v[150:151], v[188:189], v[244:245]
	v_pk_fma_f32 v[246:247], v[152:153], v[190:191], v[246:247]
	v_pk_fma_f32 v[188:189], v[16:17], v[188:189], v[244:245] op_sel:[0,1,0] op_sel_hi:[1,0,1]
	v_pk_fma_f32 v[190:191], v[36:37], v[190:191], v[246:247] op_sel:[0,1,0] op_sel_hi:[1,0,1]
	v_cvt_pk_bf16_f32 v119, v188, v189
	v_cvt_pk_bf16_f32 v131, v190, v191
	ds_write_b32 v103, v119 offset:3536
	ds_write_b32 v103, v131 offset:4896
	v_pk_fma_f32 v[250:251], v[150:151], v[188:189], v[250:251]
	s_waitcnt lgkmcnt(15)
; __device__ __forceinline__ void s5_out_phase(LAS unsigned char* lds, const bf16_t* UZ, const unsigned char* ws, const float* dskip, bf16_t* YG) {
;     ...
;             for (int nt = 0; nt < 8; ++nt) {
;                 const f32x4 z = {0.f, 0.f, 0.f, 0.f};
;                 const f32x4 cf = __builtin_amdgcn_mfma_f32_16x16x16bf16_1k(Uf[mf], Bf[0][nt], z, 0, 0, 0);
;                 const f32x4 cb = __builtin_amdgcn_mfma_f32_16x16x16bf16_1k(Uf[mb], Bf[1][nt], z, 0, 0, 0);
;                 u32x2 wf, wb; wf.x = pk2(cf[0], cf[1]); wf.y = pk2(cf[2], cf[3]); wb.x = pk2(cb[0], cb[1]); wb.y = pk2(cb[2], cb[3]);
;                 *(LAS u32x2*)(wl + nt * 640 + wofs) = wf;
;                 *(LAS u32x2*)(wl + BUT_BYTES + nt * 640 + wofs) = wb;
;             }
;             WAVE_LDS_FENCE();
;             const LAS unsigned char* rp = wl + lane * 80;
;             const u32x4 fre0 = *(const LAS u32x4*)(rp), fre1 = *(const LAS u32x4*)(rp + 16), fim0 = *(const LAS u32x4*)(rp + 32), fim1 = *(const LAS u32x4*)(rp + 48);
;             const u32x4 bre0 = *(const LAS u32x4*)(rp + BUT_BYTES), bre1 = *(const LAS u32x4*)(rp + BUT_BYTES + 16), bim0 = *(const LAS u32x4*)(rp + BUT_BYTES + 32), bim1 = *(const LAS u32x4*)(rp + BUT_BYTES + 48);
;             LAS unsigned char* xf = wl + 2 * BUT_BYTES; LAS unsigned char* xbk = xf + XB_BYTES;
; #pragma unroll
;             for (int rr = 0; rr < 16; ++rr) {
;                 const int r = rr, rb = 15 - rr;
;                 { const f32x2 bb = {bf_at(fre0, fre1, r), bf_at(fim0, fim1, r)};
;                   const f32x2 n2 = cmac((f32x2){xfr, xfi}, (f32x2){ap[0].x, ap[0].x}, (f32x2){-ap[0].y, ap[0].y}, bb); xfr = n2.x; xfi = n2.y;
;                   *(LAS unsigned*)(xf + r * XB_PITCH + lane * 4) = pk2(n2.x, n2.y); }
;                 { const f32x2 bb = {bf_at(bre0, bre1, rb), bf_at(bim0, bim1, rb)};
;                   const f32x2 n2 = cmac((f32x2){xbr, xbi}, (f32x2){ap[1].x, ap[1].x}, (f32x2){-ap[1].y, ap[1].y}, bb); xbr = n2.x; xbi = n2.y;
;                   *(LAS unsigned*)(xbk + rb * XB_PITCH + lane * 4) = pk2(n2.x, n2.y); }
;             }
;             WAVE_LDS_FENCE();
; #pragma unroll
;             for (int ks = 0; ks < 4; ++ks) {
;                 const bf16x8 Xf = *(const LAS bf16x8*)(xf + fr * XB_PITCH + (8 * fq + 32 * ks) * 2);
;                 const bf16x8 Xb = *(const LAS bf16x8*)(xbk + fr * XB_PITCH + (8 * fq + 32 * ks) * 2);
	v_pk_fma_f32 v[196:197], v[152:153], v[190:191], v[196:197]
	v_pk_fma_f32 v[188:189], v[16:17], v[188:189], v[250:251] op_sel:[0,1,0] op_sel_hi:[1,0,1]
	v_pk_fma_f32 v[190:191], v[36:37], v[190:191], v[196:197] op_sel:[0,1,0] op_sel_hi:[1,0,1]
	v_cvt_pk_bf16_f32 v121, v188, v189
	v_cvt_pk_bf16_f32 v132, v190, v191
	ds_write_b32 v103, v121 offset:3808
	ds_write_b32 v103, v132 offset:4624
	v_pk_fma_f32 v[252:253], v[150:151], v[188:189], v[252:253]
	v_pk_fma_f32 v[194:195], v[152:153], v[190:191], v[194:195]
	v_pk_fma_f32 v[188:189], v[16:17], v[188:189], v[252:253] op_sel:[0,1,0] op_sel_hi:[1,0,1]
	v_pk_fma_f32 v[190:191], v[36:37], v[190:191], v[194:195] op_sel:[0,1,0] op_sel_hi:[1,0,1]
	v_cvt_pk_bf16_f32 v127, v188, v189
	v_cvt_pk_bf16_f32 v135, v190, v191
	ds_write_b32 v103, v127 offset:4080
	ds_write_b32 v103, v135 offset:4352
	ds_read_b128 v[194:197], v110
	ds_read_b128 v[198:201], v110 offset:64
	ds_read_b128 v[202:205], v110 offset:128
	ds_read_b128 v[206:209], v110 offset:192
	ds_read_b128 v[210:213], v110 offset:4352
	ds_read_b128 v[214:217], v110 offset:4416
	ds_read_b128 v[218:221], v110 offset:4480
	ds_read_b128 v[222:225], v110 offset:4544
	v_mfma_f32_16x16x16_bf16 v[226:229], v[60:61], v[116:117], 0
	v_mfma_f32_16x16x16_bf16 v[230:233], v[76:77], v[172:173], 0
	v_mfma_f32_16x16x16_bf16 v[234:237], v[62:63], v[116:117], 0
	v_mfma_f32_16x16x16_bf16 v[238:241], v[78:79], v[172:173], 0
	s_nop 4
	ds_write_b64 v136, v[226:227]
	s_nop 2
	ds_write_b64 v136, v[228:229] offset:144
	v_mfma_f32_16x16x16_bf16 v[242:245], v[64:65], v[116:117], 0
	s_nop 0
	ds_write_b64 v136, v[230:231] offset:9216
	ds_write_b64 v136, v[232:233] offset:9360
	v_mfma_f32_16x16x16_bf16 v[246:249], v[80:81], v[172:173], 0
	ds_write_b64 v136, v[234:235] offset:1152
	ds_write_b64 v136, v[236:237] offset:1296
	v_mfma_f32_16x16x16_bf16 v[226:229], v[66:67], v[116:117], 0
	ds_write_b64 v136, v[238:239] offset:10368
	ds_write_b64 v136, v[240:241] offset:10512
	v_mfma_f32_16x16x16_bf16 v[230:233], v[82:83], v[172:173], 0
	ds_write_b64 v136, v[242:243] offset:2304
	ds_write_b64 v136, v[244:245] offset:2448
	v_mfma_f32_16x16x16_bf16 v[234:237], v[68:69], v[116:117], 0
	ds_write_b64 v136, v[246:247] offset:11520
	ds_write_b64 v136, v[248:249] offset:11664
	v_mfma_f32_16x16x16_bf16 v[238:241], v[84:85], v[172:173], 0
	ds_write_b64 v136, v[226:227] offset:3456
	ds_write_b64 v136, v[228:229] offset:3600
	v_mfma_f32_16x16x16_bf16 v[242:245], v[70:71], v[116:117], 0
	ds_write_b64 v136, v[230:231] offset:12672
	ds_write_b64 v136, v[232:233] offset:12816
	v_mfma_f32_16x16x16_bf16 v[246:249], v[86:87], v[172:173], 0
	ds_write_b64 v136, v[234:235] offset:4608
	ds_write_b64 v136, v[236:237] offset:4752
	v_mfma_f32_16x16x16_bf16 v[226:229], v[72:73], v[116:117], 0
	ds_write_b64 v136, v[238:239] offset:13824
	ds_write_b64 v136, v[240:241] offset:13968
	v_mfma_f32_16x16x16_bf16 v[230:233], v[88:89], v[172:173], 0
	ds_write_b64 v136, v[242:243] offset:5760
	ds_write_b64 v136, v[244:245] offset:5904
	v_mfma_f32_16x16x16_bf16 v[234:237], v[74:75], v[116:117], 0
	ds_write_b64 v136, v[246:247] offset:14976
	ds_write_b64 v136, v[248:249] offset:15120
	v_mfma_f32_16x16x16_bf16 v[238:241], v[90:91], v[172:173], 0
	ds_write_b64 v136, v[226:227] offset:6912
	ds_write_b64 v136, v[228:229] offset:7056
	ds_write_b64 v136, v[230:231] offset:16128
	ds_write_b64 v136, v[232:233] offset:16272
	s_nop 0
	ds_write_b64 v136, v[234:235] offset:8064
	ds_write_b64 v136, v[236:237] offset:8208
	s_nop 0
	ds_write_b64 v136, v[238:239] offset:17280
	ds_write_b64 v136, v[240:241] offset:17424
	s_waitcnt lgkmcnt(15)
	v_mfma_f32_16x16x32_bf16 v[52:55], v[0:3], v[194:197], v[52:55]
	v_mfma_f32_16x16x32_bf16 v[56:59], v[20:23], v[210:213], v[56:59]
	v_mfma_f32_16x16x32_bf16 v[52:55], v[4:7], v[198:201], v[52:55]
	v_mfma_f32_16x16x32_bf16 v[56:59], v[24:27], v[214:217], v[56:59]
	v_mfma_f32_16x16x32_bf16 v[52:55], v[8:11], v[202:205], v[52:55]
	v_mfma_f32_16x16x32_bf16 v[56:59], v[28:31], v[218:221], v[56:59]
	v_mfma_f32_16x16x32_bf16 v[52:55], v[12:15], v[206:209], v[52:55]
	v_mfma_f32_16x16x32_bf16 v[56:59], v[32:35], v[222:225], v[56:59]
	ds_read_b128 v[194:197], v139
	ds_read_b128 v[198:201], v139 offset:9328
	ds_read_b128 v[202:205], v139 offset:16
	ds_read_b128 v[206:209], v139 offset:9312
	ds_read_b128 v[210:213], v139 offset:32
	ds_read_b128 v[214:217], v139 offset:9296
	ds_read_b128 v[218:221], v139 offset:48
	ds_read_b128 v[222:225], v139 offset:9280
	ds_read_b128 v[226:229], v139 offset:64
	ds_read_b128 v[230:233], v139 offset:9264
	ds_read_b128 v[234:237], v139 offset:80
	ds_read_b128 v[238:241], v139 offset:9248
	ds_read_b128 v[242:245], v139 offset:96
	ds_read_b128 v[246:249], v139 offset:9232
	ds_read_b128 v[250:253], v139 offset:112
	s_waitcnt lgkmcnt(14)
	v_pk_fma_f32 v[194:195], v[150:151], v[188:189], v[194:195]
	s_waitcnt lgkmcnt(13)
	v_pk_fma_f32 v[200:201], v[152:153], v[190:191], v[200:201]
	v_pk_fma_f32 v[188:189], v[16:17], v[188:189], v[194:195] op_sel:[0,1,0] op_sel_hi:[1,0,1]
	v_pk_fma_f32 v[190:191], v[36:37], v[190:191], v[200:201] op_sel:[0,1,0] op_sel_hi:[1,0,1]
	v_cvt_pk_bf16_f32 v114, v188, v189
	v_cvt_pk_bf16_f32 v128, v190, v191
	ds_write_b32 v103, v114
	ds_write_b32 v103, v128 offset:8432
	v_pk_fma_f32 v[196:197], v[150:151], v[188:189], v[196:197]
	v_pk_fma_f32 v[198:199], v[152:153], v[190:191], v[198:199]
	v_pk_fma_f32 v[188:189], v[16:17], v[188:189], v[196:197] op_sel:[0,1,0] op_sel_hi:[1,0,1]
	v_pk_fma_f32 v[190:191], v[36:37], v[190:191], v[198:199] op_sel:[0,1,0] op_sel_hi:[1,0,1]
	v_cvt_pk_bf16_f32 v119, v188, v189
	v_cvt_pk_bf16_f32 v131, v190, v191
	ds_write_b32 v103, v119 offset:272
	ds_write_b32 v103, v131 offset:8160
	ds_read_b128 v[194:197], v139 offset:9216
	s_waitcnt lgkmcnt(15)
; #define LAS __attribute__((address_space(3)))
; __device__ __forceinline__ unsigned pk2(float lo, float hi) { f32x2 v = {lo, hi}; nbf2 r = __builtin_convertvector(v, nbf2); return __builtin_bit_cast(unsigned, r); }
; __device__ __forceinline__ float bf_at(const u32x4& lo, const u32x4& hi, int r) { const unsigned w = (r < 8 ? lo : hi)[(r & 7) >> 1]; return (r & 1) ? bf_hi(w) : bf_lo(w); }
; __device__ __forceinline__ void s5_out_phase(LAS unsigned char* lds, const bf16_t* UZ, const unsigned char* ws, const float* dskip, bf16_t* YG) {
;     ...
;             for (int rr = 0; rr < 16; ++rr) {
;                 const int r = rr, rb = 15 - rr;
;                 { const f32x2 bb = {bf_at(fre0, fre1, r), bf_at(fim0, fim1, r)};
;                   const f32x2 n2 = cmac((f32x2){xfr, xfi}, (f32x2){ap[0].x, ap[0].x}, (f32x2){-ap[0].y, ap[0].y}, bb); xfr = n2.x; xfi = n2.y;
;                   *(LAS unsigned*)(xf + r * XB_PITCH + lane * 4) = pk2(n2.x, n2.y); }
;                 { const f32x2 bb = {bf_at(bre0, bre1, rb), bf_at(bim0, bim1, rb)};
;                   const f32x2 n2 = cmac((f32x2){xbr, xbi}, (f32x2){ap[1].x, ap[1].x}, (f32x2){-ap[1].y, ap[1].y}, bb); xbr = n2.x; xbi = n2.y;
;                   *(LAS unsigned*)(xbk + rb * XB_PITCH + lane * 4) = pk2(n2.x, n2.y); }
;             }
	v_pk_fma_f32 v[202:203], v[150:151], v[188:189], v[202:203]
	v_pk_fma_f32 v[208:209], v[152:153], v[190:191], v[208:209]
	v_pk_fma_f32 v[188:189], v[16:17], v[188:189], v[202:203] op_sel:[0,1,0] op_sel_hi:[1,0,1]
	v_pk_fma_f32 v[190:191], v[36:37], v[190:191], v[208:209] op_sel:[0,1,0] op_sel_hi:[1,0,1]
	v_cvt_pk_bf16_f32 v121, v188, v189
	v_cvt_pk_bf16_f32 v132, v190, v191
	ds_write_b32 v103, v121 offset:544
	ds_write_b32 v103, v132 offset:7888
	v_pk_fma_f32 v[204:205], v[150:151], v[188:189], v[204:205]
	v_pk_fma_f32 v[206:207], v[152:153], v[190:191], v[206:207]
	v_pk_fma_f32 v[188:189], v[16:17], v[188:189], v[204:205] op_sel:[0,1,0] op_sel_hi:[1,0,1]
	v_pk_fma_f32 v[190:191], v[36:37], v[190:191], v[206:207] op_sel:[0,1,0] op_sel_hi:[1,0,1]
	v_cvt_pk_bf16_f32 v127, v188, v189
	v_cvt_pk_bf16_f32 v135, v190, v191
	ds_write_b32 v103, v127 offset:816
	ds_write_b32 v103, v135 offset:7616
	v_pk_fma_f32 v[210:211], v[150:151], v[188:189], v[210:211]
	s_waitcnt lgkmcnt(15)
	v_pk_fma_f32 v[216:217], v[152:153], v[190:191], v[216:217]
	v_pk_fma_f32 v[188:189], v[16:17], v[188:189], v[210:211] op_sel:[0,1,0] op_sel_hi:[1,0,1]
	v_pk_fma_f32 v[190:191], v[36:37], v[190:191], v[216:217] op_sel:[0,1,0] op_sel_hi:[1,0,1]
	v_cvt_pk_bf16_f32 v114, v188, v189
	v_cvt_pk_bf16_f32 v128, v190, v191
	ds_write_b32 v103, v114 offset:1088
	ds_write_b32 v103, v128 offset:7344
	v_pk_fma_f32 v[212:213], v[150:151], v[188:189], v[212:213]
	v_pk_fma_f32 v[214:215], v[152:153], v[190:191], v[214:215]
	v_pk_fma_f32 v[188:189], v[16:17], v[188:189], v[212:213] op_sel:[0,1,0] op_sel_hi:[1,0,1]
	v_pk_fma_f32 v[190:191], v[36:37], v[190:191], v[214:215] op_sel:[0,1,0] op_sel_hi:[1,0,1]
	v_cvt_pk_bf16_f32 v119, v188, v189
	v_cvt_pk_bf16_f32 v131, v190, v191
	ds_write_b32 v103, v119 offset:1360
	ds_write_b32 v103, v131 offset:7072
	v_pk_fma_f32 v[218:219], v[150:151], v[188:189], v[218:219]
	v_pk_fma_f32 v[224:225], v[152:153], v[190:191], v[224:225]
	v_pk_fma_f32 v[188:189], v[16:17], v[188:189], v[218:219] op_sel:[0,1,0] op_sel_hi:[1,0,1]
	v_pk_fma_f32 v[190:191], v[36:37], v[190:191], v[224:225] op_sel:[0,1,0] op_sel_hi:[1,0,1]
	v_cvt_pk_bf16_f32 v121, v188, v189
	v_cvt_pk_bf16_f32 v132, v190, v191
	ds_write_b32 v103, v121 offset:1632
	ds_write_b32 v103, v132 offset:6800
	v_pk_fma_f32 v[220:221], v[150:151], v[188:189], v[220:221]
	v_pk_fma_f32 v[222:223], v[152:153], v[190:191], v[222:223]
	v_pk_fma_f32 v[188:189], v[16:17], v[188:189], v[220:221] op_sel:[0,1,0] op_sel_hi:[1,0,1]
	v_pk_fma_f32 v[190:191], v[36:37], v[190:191], v[222:223] op_sel:[0,1,0] op_sel_hi:[1,0,1]
	v_cvt_pk_bf16_f32 v127, v188, v189
	v_cvt_pk_bf16_f32 v135, v190, v191
	ds_write_b32 v103, v127 offset:1904
	ds_write_b32 v103, v135 offset:6528
	v_pk_fma_f32 v[226:227], v[150:151], v[188:189], v[226:227]
	s_waitcnt lgkmcnt(15)
	v_pk_fma_f32 v[232:233], v[152:153], v[190:191], v[232:233]
	v_pk_fma_f32 v[188:189], v[16:17], v[188:189], v[226:227] op_sel:[0,1,0] op_sel_hi:[1,0,1]
	v_pk_fma_f32 v[190:191], v[36:37], v[190:191], v[232:233] op_sel:[0,1,0] op_sel_hi:[1,0,1]
	v_cvt_pk_bf16_f32 v114, v188, v189
	v_cvt_pk_bf16_f32 v128, v190, v191
	ds_write_b32 v103, v114 offset:2176
	ds_write_b32 v103, v128 offset:6256
	v_pk_fma_f32 v[228:229], v[150:151], v[188:189], v[228:229]
	v_pk_fma_f32 v[230:231], v[152:153], v[190:191], v[230:231]
	v_pk_fma_f32 v[188:189], v[16:17], v[188:189], v[228:229] op_sel:[0,1,0] op_sel_hi:[1,0,1]
	v_pk_fma_f32 v[190:191], v[36:37], v[190:191], v[230:231] op_sel:[0,1,0] op_sel_hi:[1,0,1]
	v_cvt_pk_bf16_f32 v119, v188, v189
	v_cvt_pk_bf16_f32 v131, v190, v191
	ds_write_b32 v103, v119 offset:2448
	ds_write_b32 v103, v131 offset:5984
	v_pk_fma_f32 v[234:235], v[150:151], v[188:189], v[234:235]
	v_pk_fma_f32 v[240:241], v[152:153], v[190:191], v[240:241]
	v_pk_fma_f32 v[188:189], v[16:17], v[188:189], v[234:235] op_sel:[0,1,0] op_sel_hi:[1,0,1]
	v_pk_fma_f32 v[190:191], v[36:37], v[190:191], v[240:241] op_sel:[0,1,0] op_sel_hi:[1,0,1]
	v_cvt_pk_bf16_f32 v121, v188, v189
	v_cvt_pk_bf16_f32 v132, v190, v191
	ds_write_b32 v103, v121 offset:2720
	ds_write_b32 v103, v132 offset:5712
	v_pk_fma_f32 v[236:237], v[150:151], v[188:189], v[236:237]
	v_pk_fma_f32 v[238:239], v[152:153], v[190:191], v[238:239]
	v_pk_fma_f32 v[188:189], v[16:17], v[188:189], v[236:237] op_sel:[0,1,0] op_sel_hi:[1,0,1]
	v_pk_fma_f32 v[190:191], v[36:37], v[190:191], v[238:239] op_sel:[0,1,0] op_sel_hi:[1,0,1]
	v_cvt_pk_bf16_f32 v127, v188, v189
	v_cvt_pk_bf16_f32 v135, v190, v191
	ds_write_b32 v103, v127 offset:2992
	ds_write_b32 v103, v135 offset:5440
	v_pk_fma_f32 v[242:243], v[150:151], v[188:189], v[242:243]
	v_pk_fma_f32 v[248:249], v[152:153], v[190:191], v[248:249]
	v_pk_fma_f32 v[188:189], v[16:17], v[188:189], v[242:243] op_sel:[0,1,0] op_sel_hi:[1,0,1]
	v_pk_fma_f32 v[190:191], v[36:37], v[190:191], v[248:249] op_sel:[0,1,0] op_sel_hi:[1,0,1]
	v_cvt_pk_bf16_f32 v114, v188, v189
	v_cvt_pk_bf16_f32 v128, v190, v191
	ds_write_b32 v103, v114 offset:3264
	ds_write_b32 v103, v128 offset:5168
	v_pk_fma_f32 v[244:245], v[150:151], v[188:189], v[244:245]
	v_pk_fma_f32 v[246:247], v[152:153], v[190:191], v[246:247]
	v_pk_fma_f32 v[188:189], v[16:17], v[188:189], v[244:245] op_sel:[0,1,0] op_sel_hi:[1,0,1]
	v_pk_fma_f32 v[190:191], v[36:37], v[190:191], v[246:247] op_sel:[0,1,0] op_sel_hi:[1,0,1]
	v_cvt_pk_bf16_f32 v119, v188, v189
	v_cvt_pk_bf16_f32 v131, v190, v191
	ds_write_b32 v103, v119 offset:3536
	ds_write_b32 v103, v131 offset:4896
	v_pk_fma_f32 v[250:251], v[150:151], v[188:189], v[250:251]
	s_waitcnt lgkmcnt(15)
; #define LAS __attribute__((address_space(3)))
; __device__ __forceinline__ unsigned pk2(float lo, float hi) { f32x2 v = {lo, hi}; nbf2 r = __builtin_convertvector(v, nbf2); return __builtin_bit_cast(unsigned, r); }
; __device__ __forceinline__ float bf_lo(unsigned w) { return __uint_as_float(w << 16); }
; __device__ __forceinline__ float bf_hi(unsigned w) { return __uint_as_float(w & 0xffff0000u); }
; __device__ __forceinline__ float fast_rcp(float x) { return __builtin_amdgcn_rcpf(x); }
; __device__ __forceinline__ float fast_exp2(float x) { return __builtin_amdgcn_exp2f(x); }
; __device__ __forceinline__ float gelu_f(float v) {
;     const float av = fabsf(v), d = av * 0.2316418882f + 1.0f;
;     const float t = fast_rcp(d);
;     float q = t * 0.5307027145f + (-0.7265760135f); q = q * t + 0.7107068705f; q = q * t + (-0.142248368f); q = q * t + 0.127414796f; q = q * t;
;     const float e = fast_exp2((v * v) * (-0.72134752044f));
;     const float m = v * (q * e), r = v - m;
;     return v < 0.f ? m : r;
; }
; __device__ __forceinline__ void s5_out_phase(LAS unsigned char* lds, const bf16_t* UZ, const unsigned char* ws, const float* dskip, bf16_t* YG) {
;     ...
;             for (int ks = 0; ks < 4; ++ks) {
;                 const bf16x8 Xf = *(const LAS bf16x8*)(xf + fr * XB_PITCH + (8 * fq + 32 * ks) * 2);
;                 const bf16x8 Xb = *(const LAS bf16x8*)(xbk + fr * XB_PITCH + (8 * fq + 32 * ks) * 2);
;                 accY[mf] = __builtin_amdgcn_mfma_f32_16x16x32_bf16(Cf[0][ks], Xf, accY[mf], 0, 0, 0);
;                 accY[mb] = __builtin_amdgcn_mfma_f32_16x16x32_bf16(Cf[1][ks], Xb, accY[mb], 0, 0, 0);
;             }
;         }
; #pragma unroll
;         for (int m = 0; m < 4; ++m) {
;             const unsigned u0 = (unsigned)(unsigned short)Uf[m][0] | ((unsigned)(unsigned short)Uf[m][1] << 16), u1 = (unsigned)(unsigned short)Uf[m][2] | ((unsigned)(unsigned short)Uf[m][3] << 16);
;             const float y0 = gelu_f(accY[m][0] + dsk[0] * bf_lo(u0)), y1 = gelu_f(accY[m][1] + dsk[1] * bf_hi(u0));
;             const float y2 = gelu_f(accY[m][2] + dsk[2] * bf_lo(u1)), y3 = gelu_f(accY[m][3] + dsk[3] * bf_hi(u1));
;             u32x2 w; w.x = pk2(y0, y1); w.y = pk2(y2, y3);
;             *(u32x2*)(YG + (size_t)(rowbase + 16 * m + fr) * D + 16 * g + 4 * fq) = w;
;         }
	v_pk_fma_f32 v[196:197], v[152:153], v[190:191], v[196:197]
	v_pk_fma_f32 v[188:189], v[16:17], v[188:189], v[250:251] op_sel:[0,1,0] op_sel_hi:[1,0,1]
	v_pk_fma_f32 v[190:191], v[36:37], v[190:191], v[196:197] op_sel:[0,1,0] op_sel_hi:[1,0,1]
	v_cvt_pk_bf16_f32 v121, v188, v189
	v_cvt_pk_bf16_f32 v132, v190, v191
	ds_write_b32 v103, v121 offset:3808
	ds_write_b32 v103, v132 offset:4624
	v_pk_fma_f32 v[252:253], v[150:151], v[188:189], v[252:253]
	v_pk_fma_f32 v[194:195], v[152:153], v[190:191], v[194:195]
	v_pk_fma_f32 v[188:189], v[16:17], v[188:189], v[252:253] op_sel:[0,1,0] op_sel_hi:[1,0,1]
	v_pk_fma_f32 v[190:191], v[36:37], v[190:191], v[194:195] op_sel:[0,1,0] op_sel_hi:[1,0,1]
	v_cvt_pk_bf16_f32 v127, v188, v189
	v_cvt_pk_bf16_f32 v135, v190, v191
	ds_write_b32 v103, v127 offset:4080
	ds_write_b32 v103, v135 offset:4352
	ds_read_b128 v[194:197], v110
	ds_read_b128 v[198:201], v110 offset:64
	ds_read_b128 v[202:205], v110 offset:128
	ds_read_b128 v[206:209], v110 offset:192
	ds_read_b128 v[210:213], v110 offset:4352
	ds_read_b128 v[214:217], v110 offset:4416
	ds_read_b128 v[218:221], v110 offset:4480
	ds_read_b128 v[222:225], v110 offset:4544
	s_waitcnt lgkmcnt(7)
	v_mfma_f32_16x16x32_bf16 v[44:47], v[0:3], v[194:197], v[44:47]
	s_waitcnt lgkmcnt(3)
	v_mfma_f32_16x16x32_bf16 v[48:51], v[20:23], v[210:213], v[48:51]
	v_mfma_f32_16x16x32_bf16 v[44:47], v[4:7], v[198:201], v[44:47]
	s_waitcnt lgkmcnt(2)
	v_mfma_f32_16x16x32_bf16 v[48:51], v[24:27], v[214:217], v[48:51]
	v_mfma_f32_16x16x32_bf16 v[44:47], v[8:11], v[202:205], v[44:47]
	s_waitcnt lgkmcnt(1)
	v_mfma_f32_16x16x32_bf16 v[48:51], v[28:31], v[218:221], v[48:51]
	v_mfma_f32_16x16x32_bf16 v[44:47], v[12:15], v[206:209], v[44:47]
	s_waitcnt lgkmcnt(0)
	v_mfma_f32_16x16x32_bf16 v[48:51], v[32:35], v[222:225], v[48:51]
	v_ashrrev_i32_e32 v167, 31, v166
	s_nop 7
	s_nop 4
	v_lshlrev_b32_e32 v188, 16, v172
	v_and_b32_e32 v189, 0xffff0000, v172
	s_waitcnt vmcnt(0)
	v_pk_fma_f32 v[188:189], v[40:41], v[188:189], v[48:49]
	v_lshlrev_b32_e32 v172, 16, v173
	v_fma_f32 v48, |v188|, s21, 1.0
	v_rcp_f32_e32 v190, v48
	v_fma_f32 v48, |v189|, s21, 1.0
	v_rcp_f32_e32 v191, v48
	v_pk_mul_f32 v[194:195], v[188:189], v[188:189]
	v_and_b32_e32 v173, 0xffff0000, v173
	v_mul_f32_e32 v48, 0xbf38aa3b, v194
	v_exp_f32_e32 v194, v48
	v_mov_b64_e32 v[48:49], s[4:5]
	v_pk_fma_f32 v[196:197], v[190:191], s[2:3], v[48:49] op_sel_hi:[1,0,0]
	v_mul_f32_e32 v114, 0xbf38aa3b, v195
	v_pk_fma_f32 v[196:197], v[190:191], v[196:197], s[8:9] op_sel_hi:[1,1,0]
	v_exp_f32_e32 v195, v114
	v_pk_fma_f32 v[196:197], v[190:191], v[196:197], s[20:21] op_sel_hi:[1,1,0]
	v_pk_fma_f32 v[50:51], v[42:43], v[172:173], v[50:51]
	v_pk_fma_f32 v[196:197], v[190:191], v[196:197], s[22:23] op_sel_hi:[1,1,0]
	v_fma_f32 v121, |v50|, s21, 1.0
	v_pk_mul_f32 v[190:191], v[190:191], v[196:197]
	v_rcp_f32_e32 v172, v121
	v_fma_f32 v121, |v51|, s21, 1.0
	v_pk_mul_f32 v[190:191], v[194:195], v[190:191]
	v_rcp_f32_e32 v173, v121
	v_pk_mul_f32 v[194:195], v[188:189], v[190:191]
	v_pk_fma_f32 v[190:191], v[188:189], v[190:191], v[188:189] neg_lo:[1,0,0] neg_hi:[1,0,0]
	v_cmp_gt_f32_e32 vcc, 0, v189
	s_nop 1
	v_cndmask_b32_e32 v114, v191, v195, vcc
	v_cmp_gt_f32_e32 vcc, 0, v188
	v_pk_mul_f32 v[188:189], v[50:51], v[50:51]
	s_nop 0
	v_mul_f32_e32 v121, 0xbf38aa3b, v188
	v_cndmask_b32_e32 v119, v190, v194, vcc
	v_exp_f32_e32 v188, v121
	v_pk_fma_f32 v[190:191], v[172:173], s[2:3], v[48:49] op_sel_hi:[1,0,0]
	v_mul_f32_e32 v121, 0xbf38aa3b, v189
	v_pk_fma_f32 v[190:191], v[172:173], v[190:191], s[8:9] op_sel_hi:[1,1,0]
	v_exp_f32_e32 v189, v121
	v_pk_fma_f32 v[190:191], v[172:173], v[190:191], s[20:21] op_sel_hi:[1,1,0]
	v_cmp_gt_f32_e32 vcc, 0, v51
	v_pk_fma_f32 v[190:191], v[172:173], v[190:191], s[22:23] op_sel_hi:[1,1,0]
	s_nop 0
	v_pk_mul_f32 v[172:173], v[172:173], v[190:191]
	s_nop 0
	v_pk_mul_f32 v[172:173], v[188:189], v[172:173]
	s_nop 0
	v_pk_mul_f32 v[188:189], v[50:51], v[172:173]
	v_pk_fma_f32 v[172:173], v[50:51], v[172:173], v[50:51] neg_lo:[1,0,0] neg_hi:[1,0,0]
	s_nop 0
	v_cndmask_b32_e32 v51, v173, v189, vcc
	v_cmp_gt_f32_e32 vcc, 0, v50
	v_cvt_pk_bf16_f32 v50, v119, v114
	s_nop 0
	v_cndmask_b32_e32 v121, v172, v188, vcc
	v_lshlrev_b64 v[172:173], 11, v[166:167]
	v_cvt_pk_bf16_f32 v51, v121, v51
	v_lshl_add_u64 v[172:173], v[154:155], 0, v[172:173]
	global_store_dwordx2 v[172:173], v[50:51], off
	v_lshlrev_b32_e32 v50, 16, v170
	v_and_b32_e32 v51, 0xffff0000, v170
	v_pk_fma_f32 v[50:51], v[40:41], v[50:51], v[56:57]
	s_nop 0
	v_fma_f32 v56, |v50|, s21, 1.0
	v_fma_f32 v57, |v51|, s21, 1.0
	v_rcp_f32_e32 v56, v56
	v_rcp_f32_e32 v57, v57
	v_pk_mul_f32 v[172:173], v[50:51], v[50:51]
	v_cmp_gt_f32_e32 vcc, 0, v51
	v_mul_f32_e32 v114, 0xbf38aa3b, v172
	v_exp_f32_e32 v172, v114
	v_pk_fma_f32 v[188:189], v[56:57], s[2:3], v[48:49] op_sel_hi:[1,0,0]
	v_mul_f32_e32 v114, 0xbf38aa3b, v173
	v_pk_fma_f32 v[188:189], v[56:57], v[188:189], s[8:9] op_sel_hi:[1,1,0]
	v_exp_f32_e32 v173, v114
	v_pk_fma_f32 v[188:189], v[56:57], v[188:189], s[20:21] op_sel_hi:[1,1,0]
	s_nop 0
	v_pk_fma_f32 v[188:189], v[56:57], v[188:189], s[22:23] op_sel_hi:[1,1,0]
	s_nop 0
	v_pk_mul_f32 v[56:57], v[56:57], v[188:189]
	s_nop 0
	v_pk_mul_f32 v[56:57], v[172:173], v[56:57]
	s_nop 0
	v_pk_mul_f32 v[172:173], v[50:51], v[56:57]
	v_pk_fma_f32 v[56:57], v[50:51], v[56:57], v[50:51] neg_lo:[1,0,0] neg_hi:[1,0,0]
	v_and_b32_e32 v51, 0xffff0000, v171
	v_cndmask_b32_e32 v114, v57, v173, vcc
	v_cmp_gt_f32_e32 vcc, 0, v50
	v_lshlrev_b32_e32 v50, 16, v171
	v_pk_fma_f32 v[50:51], v[42:43], v[50:51], v[58:59]
	v_cndmask_b32_e32 v119, v56, v172, vcc
	v_fma_f32 v56, |v50|, s21, 1.0
; __device__ __forceinline__ unsigned pk2(float lo, float hi) { f32x2 v = {lo, hi}; nbf2 r = __builtin_convertvector(v, nbf2); return __builtin_bit_cast(unsigned, r); }
; __device__ __forceinline__ float bf_lo(unsigned w) { return __uint_as_float(w << 16); }
; __device__ __forceinline__ float bf_hi(unsigned w) { return __uint_as_float(w & 0xffff0000u); }
; __device__ __forceinline__ float fast_rcp(float x) { return __builtin_amdgcn_rcpf(x); }
; __device__ __forceinline__ float fast_exp2(float x) { return __builtin_amdgcn_exp2f(x); }
; __device__ __forceinline__ float gelu_f(float v) {
;     const float av = fabsf(v), d = av * 0.2316418882f + 1.0f;
;     const float t = fast_rcp(d);
;     float q = t * 0.5307027145f + (-0.7265760135f); q = q * t + 0.7107068705f; q = q * t + (-0.142248368f); q = q * t + 0.127414796f; q = q * t;
;     const float e = fast_exp2((v * v) * (-0.72134752044f));
;     const float m = v * (q * e), r = v - m;
;     return v < 0.f ? m : r;
; }
; __device__ __forceinline__ void s5_out_phase(LAS unsigned char* lds, const bf16_t* UZ, const unsigned char* ws, const float* dskip, bf16_t* YG) {
;     ...
; #pragma unroll
;         for (int m = 0; m < 4; ++m) {
;             const unsigned u0 = (unsigned)(unsigned short)Uf[m][0] | ((unsigned)(unsigned short)Uf[m][1] << 16), u1 = (unsigned)(unsigned short)Uf[m][2] | ((unsigned)(unsigned short)Uf[m][3] << 16);
;             const float y0 = gelu_f(accY[m][0] + dsk[0] * bf_lo(u0)), y1 = gelu_f(accY[m][1] + dsk[1] * bf_hi(u0));
;             const float y2 = gelu_f(accY[m][2] + dsk[2] * bf_lo(u1)), y3 = gelu_f(accY[m][3] + dsk[3] * bf_hi(u1));
;             u32x2 w; w.x = pk2(y0, y1); w.y = pk2(y2, y3);
;             *(u32x2*)(YG + (size_t)(rowbase + 16 * m + fr) * D + 16 * g + 4 * fq) = w;
;         }
	v_fma_f32 v57, |v51|, s21, 1.0
	v_rcp_f32_e32 v56, v56
	v_rcp_f32_e32 v57, v57
	v_pk_mul_f32 v[58:59], v[50:51], v[50:51]
	v_cmp_gt_f32_e32 vcc, 0, v51
	v_mul_f32_e32 v58, 0xbf38aa3b, v58
	v_pk_fma_f32 v[170:171], v[56:57], s[2:3], v[48:49] op_sel_hi:[1,0,0]
	v_mul_f32_e32 v59, 0xbf38aa3b, v59
	v_exp_f32_e32 v58, v58
	v_pk_fma_f32 v[170:171], v[56:57], v[170:171], s[8:9] op_sel_hi:[1,1,0]
	v_exp_f32_e32 v59, v59
	v_pk_fma_f32 v[170:171], v[56:57], v[170:171], s[20:21] op_sel_hi:[1,1,0]
	v_mov_b64_e32 v[172:173], v[174:175]
	v_pk_fma_f32 v[170:171], v[56:57], v[170:171], s[22:23] op_sel_hi:[1,1,0]
	s_nop 0
	v_pk_mul_f32 v[56:57], v[56:57], v[170:171]
	v_mov_b64_e32 v[170:171], v[176:177]
	v_pk_mul_f32 v[56:57], v[58:59], v[56:57]
	s_nop 0
	v_pk_mul_f32 v[58:59], v[50:51], v[56:57]
	v_pk_fma_f32 v[56:57], v[50:51], v[56:57], v[50:51] neg_lo:[1,0,0] neg_hi:[1,0,0]
	s_nop 0
	v_cndmask_b32_e32 v51, v57, v59, vcc
	v_cmp_gt_f32_e32 vcc, 0, v50
	v_cvt_pk_bf16_f32 v50, v119, v114
	s_nop 0
	v_cndmask_b32_e32 v56, v56, v58, vcc
	v_cvt_pk_bf16_f32 v51, v56, v51
	v_add_u32_e32 v56, 16, v166
	v_ashrrev_i32_e32 v57, 31, v56
	v_lshlrev_b64 v[56:57], 11, v[56:57]
	v_lshl_add_u64 v[56:57], v[154:155], 0, v[56:57]
	global_store_dwordx2 v[56:57], v[50:51], off
	v_lshlrev_b32_e32 v50, 16, v168
	v_and_b32_e32 v51, 0xffff0000, v168
	v_pk_fma_f32 v[50:51], v[40:41], v[50:51], v[52:53]
	s_nop 0
	v_fma_f32 v52, |v50|, s21, 1.0
	v_fma_f32 v53, |v51|, s21, 1.0
	v_rcp_f32_e32 v52, v52
	v_rcp_f32_e32 v53, v53
	v_pk_mul_f32 v[56:57], v[50:51], v[50:51]
	v_cmp_gt_f32_e32 vcc, 0, v51
	v_mul_f32_e32 v56, 0xbf38aa3b, v56
	v_pk_fma_f32 v[58:59], v[52:53], s[2:3], v[48:49] op_sel_hi:[1,0,0]
	v_mul_f32_e32 v57, 0xbf38aa3b, v57
	v_exp_f32_e32 v56, v56
	v_pk_fma_f32 v[58:59], v[52:53], v[58:59], s[8:9] op_sel_hi:[1,1,0]
	v_exp_f32_e32 v57, v57
	v_pk_fma_f32 v[58:59], v[52:53], v[58:59], s[20:21] op_sel_hi:[1,1,0]
	s_nop 0
	v_pk_fma_f32 v[58:59], v[52:53], v[58:59], s[22:23] op_sel_hi:[1,1,0]
	s_nop 0
	v_pk_mul_f32 v[52:53], v[52:53], v[58:59]
	s_nop 0
	v_pk_mul_f32 v[52:53], v[56:57], v[52:53]
	s_nop 0
	v_pk_mul_f32 v[56:57], v[50:51], v[52:53]
	v_pk_fma_f32 v[52:53], v[50:51], v[52:53], v[50:51] neg_lo:[1,0,0] neg_hi:[1,0,0]
	v_and_b32_e32 v51, 0xffff0000, v169
	v_cndmask_b32_e32 v58, v53, v57, vcc
	v_cmp_gt_f32_e32 vcc, 0, v50
	v_lshlrev_b32_e32 v50, 16, v169
	v_pk_fma_f32 v[50:51], v[42:43], v[50:51], v[54:55]
	v_cndmask_b32_e32 v59, v52, v56, vcc
	v_fma_f32 v52, |v50|, s21, 1.0
	v_fma_f32 v53, |v51|, s21, 1.0
	v_rcp_f32_e32 v52, v52
	v_rcp_f32_e32 v53, v53
	v_pk_mul_f32 v[54:55], v[50:51], v[50:51]
	v_cmp_gt_f32_e32 vcc, 0, v51
	v_mul_f32_e32 v54, 0xbf38aa3b, v54
	v_pk_fma_f32 v[56:57], v[52:53], s[2:3], v[48:49] op_sel_hi:[1,0,0]
	v_mul_f32_e32 v55, 0xbf38aa3b, v55
	v_exp_f32_e32 v54, v54
	v_pk_fma_f32 v[56:57], v[52:53], v[56:57], s[8:9] op_sel_hi:[1,1,0]
	v_exp_f32_e32 v55, v55
	v_pk_fma_f32 v[56:57], v[52:53], v[56:57], s[20:21] op_sel_hi:[1,1,0]
	v_mov_b64_e32 v[168:169], v[178:179]
	v_pk_fma_f32 v[56:57], v[52:53], v[56:57], s[22:23] op_sel_hi:[1,1,0]
	s_nop 0
	v_pk_mul_f32 v[52:53], v[52:53], v[56:57]
	s_nop 0
	v_pk_mul_f32 v[52:53], v[54:55], v[52:53]
	s_nop 0
	v_pk_mul_f32 v[54:55], v[50:51], v[52:53]
	v_pk_fma_f32 v[52:53], v[50:51], v[52:53], v[50:51] neg_lo:[1,0,0] neg_hi:[1,0,0]
	s_nop 0
	v_cndmask_b32_e32 v51, v53, v55, vcc
	v_cmp_gt_f32_e32 vcc, 0, v50
	v_cvt_pk_bf16_f32 v50, v59, v58
	s_nop 0
	v_cndmask_b32_e32 v52, v52, v54, vcc
	v_cvt_pk_bf16_f32 v51, v52, v51
	v_add_u32_e32 v52, 32, v166
	v_ashrrev_i32_e32 v53, 31, v52
	v_lshlrev_b64 v[52:53], 11, v[52:53]
	v_lshl_add_u64 v[52:53], v[154:155], 0, v[52:53]
	global_store_dwordx2 v[52:53], v[50:51], off
	v_lshlrev_b32_e32 v50, 16, v116
	v_and_b32_e32 v51, 0xffff0000, v116
	v_pk_fma_f32 v[44:45], v[40:41], v[50:51], v[44:45]
	s_nop 0
	v_fma_f32 v50, |v44|, s21, 1.0
	v_fma_f32 v51, |v45|, s21, 1.0
	v_rcp_f32_e32 v50, v50
	v_rcp_f32_e32 v51, v51
	v_pk_mul_f32 v[52:53], v[44:45], v[44:45]
	v_cmp_gt_f32_e32 vcc, 0, v45
	v_mul_f32_e32 v52, 0xbf38aa3b, v52
	v_pk_fma_f32 v[54:55], v[50:51], s[2:3], v[48:49] op_sel_hi:[1,0,0]
	v_mul_f32_e32 v53, 0xbf38aa3b, v53
	v_exp_f32_e32 v52, v52
	v_pk_fma_f32 v[54:55], v[50:51], v[54:55], s[8:9] op_sel_hi:[1,1,0]
	v_exp_f32_e32 v53, v53
	v_pk_fma_f32 v[54:55], v[50:51], v[54:55], s[20:21] op_sel_hi:[1,1,0]
	s_nop 0
	v_pk_fma_f32 v[54:55], v[50:51], v[54:55], s[22:23] op_sel_hi:[1,1,0]
	s_nop 0
	v_pk_mul_f32 v[50:51], v[50:51], v[54:55]
	s_nop 0
	v_pk_mul_f32 v[50:51], v[52:53], v[50:51]
	s_nop 0
	v_pk_mul_f32 v[52:53], v[44:45], v[50:51]
	v_pk_fma_f32 v[50:51], v[44:45], v[50:51], v[44:45] neg_lo:[1,0,0] neg_hi:[1,0,0]
	v_and_b32_e32 v45, 0xffff0000, v117
	v_cndmask_b32_e32 v53, v51, v53, vcc
	v_cmp_gt_f32_e32 vcc, 0, v44
	v_lshlrev_b32_e32 v44, 16, v117
	v_pk_fma_f32 v[44:45], v[42:43], v[44:45], v[46:47]
	v_cndmask_b32_e32 v52, v50, v52, vcc
	v_fma_f32 v46, |v44|, s21, 1.0
	v_fma_f32 v47, |v45|, s21, 1.0
	v_rcp_f32_e32 v46, v46
	v_rcp_f32_e32 v47, v47
	v_pk_mul_f32 v[50:51], v[44:45], v[44:45]
	v_cmp_gt_f32_e32 vcc, 0, v45
	v_mul_f32_e32 v50, 0xbf38aa3b, v50
	v_pk_fma_f32 v[48:49], v[46:47], s[2:3], v[48:49] op_sel_hi:[1,0,0]
	v_mul_f32_e32 v51, 0xbf38aa3b, v51
	v_exp_f32_e32 v50, v50
	v_pk_fma_f32 v[48:49], v[46:47], v[48:49], s[8:9] op_sel_hi:[1,1,0]
	v_exp_f32_e32 v51, v51
	v_pk_fma_f32 v[48:49], v[46:47], v[48:49], s[20:21] op_sel_hi:[1,1,0]
	v_mov_b64_e32 v[116:117], v[180:181]
	v_pk_fma_f32 v[48:49], v[46:47], v[48:49], s[22:23] op_sel_hi:[1,1,0]
	s_nop 0
	v_pk_mul_f32 v[46:47], v[46:47], v[48:49]
	s_nop 0
	v_pk_mul_f32 v[46:47], v[50:51], v[46:47]
	s_nop 0
	v_pk_mul_f32 v[48:49], v[44:45], v[46:47]
	v_pk_fma_f32 v[46:47], v[44:45], v[46:47], v[44:45] neg_lo:[1,0,0] neg_hi:[1,0,0]
	s_nop 0
	v_cndmask_b32_e32 v45, v47, v49, vcc
	v_cmp_gt_f32_e32 vcc, 0, v44
	v_cvt_pk_bf16_f32 v44, v52, v53
	s_nop 0
	v_cndmask_b32_e32 v46, v46, v48, vcc
	v_cvt_pk_bf16_f32 v45, v46, v45
	v_add_u32_e32 v46, 48, v166
	v_ashrrev_i32_e32 v47, 31, v46
	v_lshlrev_b64 v[46:47], 11, v[46:47]
	v_lshl_add_u64 v[46:47], v[154:155], 0, v[46:47]
	v_add_u32_e32 v166, s3, v166
	s_andn2_b64 vcc, exec, s[24:25]
	global_store_dwordx2 v[46:47], v[44:45], off
	s_cbranch_vccz .LBB0_762
